# v10b: as v10 with n-outer / m / k-inner MFMA order
# speedup vs baseline: 1.0186x; 1.0053x over previous
; #define PG8_STAGE(bufoff, gbase, voff) do { _Pragma("unroll") for (int _i = 0; _i < 2; ++_i) \
;         __builtin_amdgcn_global_load_lds((const unsigned*)((const char*)(gbase) + (voff)[_i]), (PG8_LAS unsigned*)(lds + (bufoff) + ldsw + _i * 8192), 16, 0, 0); } while (0)
; #define PG8_LDA(dst, b, h) do { _Pragma("unroll") for (int m = 0; m < 4; ++m) _Pragma("unroll") for (int k = 0; k < 2; ++k) dst[m][k] = *(const PG8_LAS bf16x8*)(lds + PG8_SA(b, h) + aoff + m * 2048 + k * 1024); } while (0)
; #define PG8_LDB(dst, b, h) do { _Pragma("unroll") for (int n = 0; n < 2; ++n) _Pragma("unroll") for (int k = 0; k < 2; ++k) dst[n][k] = *(const PG8_LAS bf16x8*)(lds + PG8_SB(b, h) + boff + n * 2048 + k * 1024); } while (0)
; #define PG8_WAIT_V(n) asm volatile("s_waitcnt vmcnt(" #n ")" ::: "memory")
; template <class Epi, class Sched, bool ALIGN_EPI = false, bool SP2 = false>
; __device__ __forceinline__ void gemm_phase(PG8_LAS unsigned char* lds, const Gemm g, const Sched& S, const Epi& E) {
;     ...
;             const char* a1 = cA + (size_t)(t + 1) * kstep;
;             const char* a2 = last ? nA : cA + (size_t)(t + 2) * kstep; const char* b2 = last ? nB : cB + (size_t)(t + 2) * kstep;
;             const char* a3 = a2 + kstep; const char* b3 = b2 + kstep;
;             if (last && has_next) S.a_ready(nxt);
;             if constexpr (SP2) {
;             PG8_LDB(B0, 0, 0); PG8_LDB(B1, 0, 1); PG8_SCHED; PG8_LDA(At, 0, 0); PG8_STAGE(PG8_SA(1, 1), a1 + hstep, voffA);
;             PG8_WAIT_V(8); PG8_WAIT_L(0); PG8_BAR; PG8_MMA(0, 0, At, B0); PG8_MMA(0, 1, At, B1); PG8_BAR; PG8_SCHED;
;             PG8_LDA(At, 0, 1); PG8_STAGE(PG8_SB(0, 0), b2, voffB); PG8_STAGE(PG8_SB(0, 1), b2 + hstep, voffB); PG8_STAGE(PG8_SA(0, 0), a2, voffA);
;             PG8_WAIT_V(8); PG8_WAIT_L(0); PG8_BAR; PG8_MMA(1, 0, At, B0); PG8_MMA(1, 1, At, B1); PG8_BAR; PG8_SCHED;
;             PG8_LDB(B0, 1, 0); PG8_LDB(B1, 1, 1); PG8_SCHED; PG8_LDA(At, 1, 0); PG8_STAGE(PG8_SA(0, 1), a2 + hstep, voffA);
;             PG8_WAIT_V(8); PG8_WAIT_L(0); PG8_BAR; PG8_MMA(0, 0, At, B0); PG8_MMA(0, 1, At, B1); PG8_BAR; PG8_SCHED;
;             PG8_LDA(At, 1, 1); PG8_STAGE(PG8_SB(1, 0), b3, voffB); PG8_STAGE(PG8_SB(1, 1), b3 + hstep, voffB); PG8_STAGE(PG8_SA(1, 0), a3, voffA);
;             PG8_WAIT_V(8); PG8_WAIT_L(0); PG8_BAR; PG8_MMA(1, 0, At, B0); PG8_MMA(1, 1, At, B1); PG8_BAR; PG8_SCHED;
.LBB0_115:
	ds_read_b128 v[154:157], v150
	ds_read_b128 v[158:161], v150 offset:1024
	ds_read_b128 v[162:165], v150 offset:2048
	ds_read_b128 v[166:169], v150 offset:3072
	ds_read_b128 v[170:173], v151
	ds_read_b128 v[174:177], v151 offset:1024
	ds_read_b128 v[180:183], v151 offset:2048
	ds_read_b128 v[184:187], v151 offset:3072
	s_add_u32 s50, s48, 0x4000
	s_addc_u32 s51, s49, 0
	s_cmp_eq_u32 s76, 60
	s_cselect_b32 s74, s64, s50
	s_cselect_b32 s75, s25, s51
	s_cselect_b32 s72, s65, s68
	s_cselect_b32 s73, s19, s69
	s_add_u32 s50, s74, 0x8000
	s_addc_u32 s51, s75, 0
	s_sub_u32 s50, s48, 0x4000
	s_subb_u32 s51, s49, 0
	v_lshl_add_u64 v[224:225], s[50:51], 0, v[130:131]
	s_mov_b32 m0, s58
	s_nop 0
	global_load_lds_dwordx4 v[224:225], off
	v_lshl_add_u64 v[224:225], s[50:51], 0, v[134:135]
	s_mov_b32 m0, s59
	s_nop 0
	global_load_lds_dwordx4 v[224:225], off
	v_lshl_add_u64 v[224:225], s[48:49], 0, v[140:141]
	s_add_i32 m0, s28, 0xc000
	ds_read_b128 v[188:191], v152
	ds_read_b128 v[196:199], v152 offset:1024
	ds_read_b128 v[200:203], v152 offset:2048
	ds_read_b128 v[204:207], v152 offset:3072
	ds_read_b128 v[208:211], v152 offset:4096
	ds_read_b128 v[212:215], v152 offset:5120
	ds_read_b128 v[216:219], v152 offset:6144
	ds_read_b128 v[220:223], v152 offset:7168
	global_load_lds_dwordx4 v[224:225], off
	v_lshl_add_u64 v[224:225], s[48:49], 0, v[142:143]
	s_add_i32 m0, s28, 0xe000
	s_nop 0
	global_load_lds_dwordx4 v[224:225], off
	s_waitcnt vmcnt(8)
	s_waitcnt lgkmcnt(0)
	s_barrier
	s_setprio 1
	s_waitcnt lgkmcnt(0)
	v_mfma_f32_16x16x32_bf16 v[126:129], v[154:157], v[188:191], v[126:129]
	v_mfma_f32_16x16x32_bf16 v[126:129], v[158:161], v[196:199], v[126:129]
	v_mfma_f32_16x16x32_bf16 v[110:113], v[154:157], v[200:203], v[110:113]
	v_mfma_f32_16x16x32_bf16 v[110:113], v[158:161], v[204:207], v[110:113]
	v_mfma_f32_16x16x32_bf16 v[94:97], v[154:157], v[208:211], v[94:97]
	v_mfma_f32_16x16x32_bf16 v[94:97], v[158:161], v[212:215], v[94:97]
	v_mfma_f32_16x16x32_bf16 v[78:81], v[154:157], v[216:219], v[78:81]
	v_mfma_f32_16x16x32_bf16 v[78:81], v[158:161], v[220:223], v[78:81]
	v_mfma_f32_16x16x32_bf16 v[118:121], v[162:165], v[188:191], v[118:121]
	v_mfma_f32_16x16x32_bf16 v[118:121], v[166:169], v[196:199], v[118:121]
	v_mfma_f32_16x16x32_bf16 v[102:105], v[162:165], v[200:203], v[102:105]
	v_mfma_f32_16x16x32_bf16 v[102:105], v[166:169], v[204:207], v[102:105]
	v_mfma_f32_16x16x32_bf16 v[86:89], v[162:165], v[208:211], v[86:89]
	v_mfma_f32_16x16x32_bf16 v[86:89], v[166:169], v[212:215], v[86:89]
	v_mfma_f32_16x16x32_bf16 v[70:73], v[162:165], v[216:219], v[70:73]
	v_mfma_f32_16x16x32_bf16 v[70:73], v[166:169], v[220:223], v[70:73]
	s_setprio 0
	s_setprio 1
	v_mfma_f32_16x16x32_bf16 v[122:125], v[170:173], v[188:191], v[122:125]
	v_mfma_f32_16x16x32_bf16 v[122:125], v[174:177], v[196:199], v[122:125]
	v_mfma_f32_16x16x32_bf16 v[106:109], v[170:173], v[200:203], v[106:109]
	v_mfma_f32_16x16x32_bf16 v[106:109], v[174:177], v[204:207], v[106:109]
	v_mfma_f32_16x16x32_bf16 v[90:93], v[170:173], v[208:211], v[90:93]
	v_mfma_f32_16x16x32_bf16 v[90:93], v[174:177], v[212:215], v[90:93]
	v_mfma_f32_16x16x32_bf16 v[74:77], v[170:173], v[216:219], v[74:77]
	v_mfma_f32_16x16x32_bf16 v[74:77], v[174:177], v[220:223], v[74:77]
	v_mfma_f32_16x16x32_bf16 v[114:117], v[180:183], v[188:191], v[114:117]
	v_mfma_f32_16x16x32_bf16 v[114:117], v[184:187], v[196:199], v[114:117]
	v_mfma_f32_16x16x32_bf16 v[98:101], v[180:183], v[200:203], v[98:101]
	v_mfma_f32_16x16x32_bf16 v[98:101], v[184:187], v[204:207], v[98:101]
	v_mfma_f32_16x16x32_bf16 v[82:85], v[180:183], v[208:211], v[82:85]
	v_mfma_f32_16x16x32_bf16 v[82:85], v[184:187], v[212:215], v[82:85]
	v_mfma_f32_16x16x32_bf16 v[66:69], v[180:183], v[216:219], v[66:69]
	v_mfma_f32_16x16x32_bf16 v[66:69], v[184:187], v[220:223], v[66:69]
	s_setprio 0
	s_barrier
	s_add_i32 s77, s61, s3
	v_lshl_add_u64 v[224:225], s[72:73], 0, v[132:133]
	s_mov_b32 m0, s77
	ds_read_b128 v[188:191], v152 offset:16384
	ds_read_b128 v[196:199], v152 offset:17408
	ds_read_b128 v[200:203], v152 offset:18432
	ds_read_b128 v[204:207], v152 offset:19456
	ds_read_b128 v[208:211], v152 offset:20480
	ds_read_b128 v[212:215], v152 offset:21504
	ds_read_b128 v[216:219], v152 offset:22528
	ds_read_b128 v[220:223], v152 offset:23552
	global_load_lds_dwordx4 v[224:225], off
	s_add_i32 m0, s77, 0x2000
	s_add_u32 s78, s72, 0x4000
	v_lshl_add_u64 v[224:225], s[72:73], 0, v[136:137]
	s_addc_u32 s79, s73, 0
	s_add_i32 s77, s62, s3
	global_load_lds_dwordx4 v[224:225], off
	v_lshl_add_u64 v[224:225], s[78:79], 0, v[132:133]
	s_mov_b32 m0, s77
	s_nop 0
	global_load_lds_dwordx4 v[224:225], off
	v_lshl_add_u64 v[224:225], s[78:79], 0, v[136:137]
	s_add_i32 m0, s77, 0x2000
	s_nop 0
	global_load_lds_dwordx4 v[224:225], off
	s_waitcnt vmcnt(6)
	s_waitcnt lgkmcnt(0)
	s_barrier
; #define PG8_STAGE(bufoff, gbase, voff) do { _Pragma("unroll") for (int _i = 0; _i < 2; ++_i) \
;         __builtin_amdgcn_global_load_lds((const unsigned*)((const char*)(gbase) + (voff)[_i]), (PG8_LAS unsigned*)(lds + (bufoff) + ldsw + _i * 8192), 16, 0, 0); } while (0)
; #define PG8_LDA(dst, b, h) do { _Pragma("unroll") for (int m = 0; m < 4; ++m) _Pragma("unroll") for (int k = 0; k < 2; ++k) dst[m][k] = *(const PG8_LAS bf16x8*)(lds + PG8_SA(b, h) + aoff + m * 2048 + k * 1024); } while (0)
; #define PG8_LDB(dst, b, h) do { _Pragma("unroll") for (int n = 0; n < 2; ++n) _Pragma("unroll") for (int k = 0; k < 2; ++k) dst[n][k] = *(const PG8_LAS bf16x8*)(lds + PG8_SB(b, h) + boff + n * 2048 + k * 1024); } while (0)
; #define PG8_MMA(ai, bj, At, Bt) do { __builtin_amdgcn_s_setprio(1); _Pragma("unroll") for (int m = 0; m < 4; ++m) _Pragma("unroll") for (int n = 0; n < 2; ++n) _Pragma("unroll") for (int k = 0; k < 2; ++k) \
;         acc[ai][bj][m][n] = __builtin_amdgcn_mfma_f32_16x16x32_bf16(Bt[n][k], At[m][k], acc[ai][bj][m][n], 0, 0, 0); __builtin_amdgcn_s_setprio(0); } while (0)
; #define PG8_BAR __builtin_amdgcn_s_barrier()
; template <class Epi, class Sched, bool ALIGN_EPI = false, bool SP2 = false>
; __device__ __forceinline__ void gemm_phase(PG8_LAS unsigned char* lds, const Gemm g, const Sched& S, const Epi& E) {
;     ...
;             if constexpr (SP2) {
;             PG8_LDB(B0, 0, 0); PG8_LDB(B1, 0, 1); PG8_SCHED; PG8_LDA(At, 0, 0); PG8_STAGE(PG8_SA(1, 1), a1 + hstep, voffA);
;             PG8_WAIT_V(8); PG8_WAIT_L(0); PG8_BAR; PG8_MMA(0, 0, At, B0); PG8_MMA(0, 1, At, B1); PG8_BAR; PG8_SCHED;
;             PG8_LDA(At, 0, 1); PG8_STAGE(PG8_SB(0, 0), b2, voffB); PG8_STAGE(PG8_SB(0, 1), b2 + hstep, voffB); PG8_STAGE(PG8_SA(0, 0), a2, voffA);
;             PG8_WAIT_V(8); PG8_WAIT_L(0); PG8_BAR; PG8_MMA(1, 0, At, B0); PG8_MMA(1, 1, At, B1); PG8_BAR; PG8_SCHED;
;             PG8_LDB(B0, 1, 0); PG8_LDB(B1, 1, 1); PG8_SCHED; PG8_LDA(At, 1, 0); PG8_STAGE(PG8_SA(0, 1), a2 + hstep, voffA);
;             PG8_WAIT_V(8); PG8_WAIT_L(0); PG8_BAR; PG8_MMA(0, 0, At, B0); PG8_MMA(0, 1, At, B1); PG8_BAR; PG8_SCHED;
;             PG8_LDA(At, 1, 1); PG8_STAGE(PG8_SB(1, 0), b3, voffB); PG8_STAGE(PG8_SB(1, 1), b3 + hstep, voffB); PG8_STAGE(PG8_SA(1, 0), a3, voffA);
;             PG8_WAIT_V(8); PG8_WAIT_L(0); PG8_BAR; PG8_MMA(1, 0, At, B0); PG8_MMA(1, 1, At, B1); PG8_BAR; PG8_SCHED;
	s_setprio 1
	s_waitcnt lgkmcnt(0)
	v_mfma_f32_16x16x32_bf16 v[62:65], v[154:157], v[188:191], v[62:65]
	v_mfma_f32_16x16x32_bf16 v[62:65], v[158:161], v[196:199], v[62:65]
	v_mfma_f32_16x16x32_bf16 v[46:49], v[154:157], v[200:203], v[46:49]
	v_mfma_f32_16x16x32_bf16 v[46:49], v[158:161], v[204:207], v[46:49]
	v_mfma_f32_16x16x32_bf16 v[30:33], v[154:157], v[208:211], v[30:33]
	v_mfma_f32_16x16x32_bf16 v[30:33], v[158:161], v[212:215], v[30:33]
	v_mfma_f32_16x16x32_bf16 v[14:17], v[154:157], v[216:219], v[14:17]
	v_mfma_f32_16x16x32_bf16 v[14:17], v[158:161], v[220:223], v[14:17]
	v_mfma_f32_16x16x32_bf16 v[54:57], v[162:165], v[188:191], v[54:57]
	v_mfma_f32_16x16x32_bf16 v[54:57], v[166:169], v[196:199], v[54:57]
	v_mfma_f32_16x16x32_bf16 v[38:41], v[162:165], v[200:203], v[38:41]
	v_mfma_f32_16x16x32_bf16 v[38:41], v[166:169], v[204:207], v[38:41]
	v_mfma_f32_16x16x32_bf16 v[22:25], v[162:165], v[208:211], v[22:25]
	v_mfma_f32_16x16x32_bf16 v[22:25], v[166:169], v[212:215], v[22:25]
	v_mfma_f32_16x16x32_bf16 v[6:9], v[162:165], v[216:219], v[6:9]
	v_mfma_f32_16x16x32_bf16 v[6:9], v[166:169], v[220:223], v[6:9]
	s_setprio 0
	s_setprio 1
	v_mfma_f32_16x16x32_bf16 v[58:61], v[170:173], v[188:191], v[58:61]
	v_mfma_f32_16x16x32_bf16 v[58:61], v[174:177], v[196:199], v[58:61]
	v_mfma_f32_16x16x32_bf16 v[42:45], v[170:173], v[200:203], v[42:45]
	v_mfma_f32_16x16x32_bf16 v[42:45], v[174:177], v[204:207], v[42:45]
	v_mfma_f32_16x16x32_bf16 v[26:29], v[170:173], v[208:211], v[26:29]
	v_mfma_f32_16x16x32_bf16 v[26:29], v[174:177], v[212:215], v[26:29]
	v_mfma_f32_16x16x32_bf16 v[10:13], v[170:173], v[216:219], v[10:13]
	v_mfma_f32_16x16x32_bf16 v[10:13], v[174:177], v[220:223], v[10:13]
	v_mfma_f32_16x16x32_bf16 v[50:53], v[180:183], v[188:191], v[50:53]
	v_mfma_f32_16x16x32_bf16 v[50:53], v[184:187], v[196:199], v[50:53]
	v_mfma_f32_16x16x32_bf16 v[34:37], v[180:183], v[200:203], v[34:37]
	v_mfma_f32_16x16x32_bf16 v[34:37], v[184:187], v[204:207], v[34:37]
	v_mfma_f32_16x16x32_bf16 v[18:21], v[180:183], v[208:211], v[18:21]
	v_mfma_f32_16x16x32_bf16 v[18:21], v[184:187], v[212:215], v[18:21]
	v_mfma_f32_16x16x32_bf16 v[2:5], v[180:183], v[216:219], v[2:5]
	v_mfma_f32_16x16x32_bf16 v[2:5], v[184:187], v[220:223], v[2:5]
	s_setprio 0
	s_barrier
	s_add_i32 s77, 0, 0x18000
	v_add_u32_e32 v138, s77, v148
	s_add_i32 s78, 0, 0x1c000
	ds_read_b128 v[154:157], v138
	ds_read_b128 v[158:161], v138 offset:1024
	ds_read_b128 v[162:165], v138 offset:2048
	ds_read_b128 v[166:169], v138 offset:3072
	v_add_u32_e32 v138, s78, v148
	ds_read_b128 v[170:173], v138
	ds_read_b128 v[174:177], v138 offset:1024
	ds_read_b128 v[180:183], v138 offset:2048
	ds_read_b128 v[184:187], v138 offset:3072
	v_lshl_add_u64 v[224:225], s[74:75], 0, v[130:131]
	s_mov_b32 m0, s28
	s_nop 0
	global_load_lds_dwordx4 v[224:225], off
	v_lshl_add_u64 v[224:225], s[74:75], 0, v[134:135]
	s_mov_b32 m0, s29
	s_nop 0
	global_load_lds_dwordx4 v[224:225], off
	s_add_u32 s74, s74, 0x4000
	s_addc_u32 s75, s75, 0
	s_mov_b32 m0, s30
	v_lshl_add_u64 v[224:225], s[74:75], 0, v[130:131]
	ds_read_b128 v[188:191], v152 offset:32768
	ds_read_b128 v[196:199], v152 offset:33792
	ds_read_b128 v[200:203], v152 offset:34816
	ds_read_b128 v[204:207], v152 offset:35840
	ds_read_b128 v[208:211], v152 offset:36864
	ds_read_b128 v[212:215], v152 offset:37888
	ds_read_b128 v[216:219], v152 offset:38912
	ds_read_b128 v[220:223], v152 offset:39936
	global_load_lds_dwordx4 v[224:225], off
	v_lshl_add_u64 v[224:225], s[74:75], 0, v[134:135]
	s_mov_b32 m0, s31
	s_nop 0
	global_load_lds_dwordx4 v[224:225], off
	s_waitcnt vmcnt(8)
	s_waitcnt lgkmcnt(0)
	s_barrier
; #define PG8_STAGE(bufoff, gbase, voff) do { _Pragma("unroll") for (int _i = 0; _i < 2; ++_i) \
;         __builtin_amdgcn_global_load_lds((const unsigned*)((const char*)(gbase) + (voff)[_i]), (PG8_LAS unsigned*)(lds + (bufoff) + ldsw + _i * 8192), 16, 0, 0); } while (0)
; #define PG8_LDA(dst, b, h) do { _Pragma("unroll") for (int m = 0; m < 4; ++m) _Pragma("unroll") for (int k = 0; k < 2; ++k) dst[m][k] = *(const PG8_LAS bf16x8*)(lds + PG8_SA(b, h) + aoff + m * 2048 + k * 1024); } while (0)
; #define PG8_LDB(dst, b, h) do { _Pragma("unroll") for (int n = 0; n < 2; ++n) _Pragma("unroll") for (int k = 0; k < 2; ++k) dst[n][k] = *(const PG8_LAS bf16x8*)(lds + PG8_SB(b, h) + boff + n * 2048 + k * 1024); } while (0)
; #define PG8_MMA(ai, bj, At, Bt) do { __builtin_amdgcn_s_setprio(1); _Pragma("unroll") for (int m = 0; m < 4; ++m) _Pragma("unroll") for (int n = 0; n < 2; ++n) _Pragma("unroll") for (int k = 0; k < 2; ++k) \
;         acc[ai][bj][m][n] = __builtin_amdgcn_mfma_f32_16x16x32_bf16(Bt[n][k], At[m][k], acc[ai][bj][m][n], 0, 0, 0); __builtin_amdgcn_s_setprio(0); } while (0)
; #define PG8_BAR __builtin_amdgcn_s_barrier()
; template <class Epi, class Sched, bool ALIGN_EPI = false, bool SP2 = false>
; __device__ __forceinline__ void gemm_phase(PG8_LAS unsigned char* lds, const Gemm g, const Sched& S, const Epi& E) {
;     ...
;             if constexpr (SP2) {
;             PG8_LDB(B0, 0, 0); PG8_LDB(B1, 0, 1); PG8_SCHED; PG8_LDA(At, 0, 0); PG8_STAGE(PG8_SA(1, 1), a1 + hstep, voffA);
;             PG8_WAIT_V(8); PG8_WAIT_L(0); PG8_BAR; PG8_MMA(0, 0, At, B0); PG8_MMA(0, 1, At, B1); PG8_BAR; PG8_SCHED;
;             PG8_LDA(At, 0, 1); PG8_STAGE(PG8_SB(0, 0), b2, voffB); PG8_STAGE(PG8_SB(0, 1), b2 + hstep, voffB); PG8_STAGE(PG8_SA(0, 0), a2, voffA);
;             PG8_WAIT_V(8); PG8_WAIT_L(0); PG8_BAR; PG8_MMA(1, 0, At, B0); PG8_MMA(1, 1, At, B1); PG8_BAR; PG8_SCHED;
;             PG8_LDB(B0, 1, 0); PG8_LDB(B1, 1, 1); PG8_SCHED; PG8_LDA(At, 1, 0); PG8_STAGE(PG8_SA(0, 1), a2 + hstep, voffA);
;             PG8_WAIT_V(8); PG8_WAIT_L(0); PG8_BAR; PG8_MMA(0, 0, At, B0); PG8_MMA(0, 1, At, B1); PG8_BAR; PG8_SCHED;
;             PG8_LDA(At, 1, 1); PG8_STAGE(PG8_SB(1, 0), b3, voffB); PG8_STAGE(PG8_SB(1, 1), b3 + hstep, voffB); PG8_STAGE(PG8_SA(1, 0), a3, voffA);
;             PG8_WAIT_V(8); PG8_WAIT_L(0); PG8_BAR; PG8_MMA(1, 0, At, B0); PG8_MMA(1, 1, At, B1); PG8_BAR; PG8_SCHED;
	s_setprio 1
	s_waitcnt lgkmcnt(0)
	v_mfma_f32_16x16x32_bf16 v[126:129], v[154:157], v[188:191], v[126:129]
	v_mfma_f32_16x16x32_bf16 v[126:129], v[158:161], v[196:199], v[126:129]
	v_mfma_f32_16x16x32_bf16 v[110:113], v[154:157], v[200:203], v[110:113]
	v_mfma_f32_16x16x32_bf16 v[110:113], v[158:161], v[204:207], v[110:113]
	v_mfma_f32_16x16x32_bf16 v[94:97], v[154:157], v[208:211], v[94:97]
	v_mfma_f32_16x16x32_bf16 v[94:97], v[158:161], v[212:215], v[94:97]
	v_mfma_f32_16x16x32_bf16 v[78:81], v[154:157], v[216:219], v[78:81]
	v_mfma_f32_16x16x32_bf16 v[78:81], v[158:161], v[220:223], v[78:81]
	v_mfma_f32_16x16x32_bf16 v[118:121], v[162:165], v[188:191], v[118:121]
	v_mfma_f32_16x16x32_bf16 v[118:121], v[166:169], v[196:199], v[118:121]
	v_mfma_f32_16x16x32_bf16 v[102:105], v[162:165], v[200:203], v[102:105]
	v_mfma_f32_16x16x32_bf16 v[102:105], v[166:169], v[204:207], v[102:105]
	v_mfma_f32_16x16x32_bf16 v[86:89], v[162:165], v[208:211], v[86:89]
	v_mfma_f32_16x16x32_bf16 v[86:89], v[166:169], v[212:215], v[86:89]
	v_mfma_f32_16x16x32_bf16 v[70:73], v[162:165], v[216:219], v[70:73]
	v_mfma_f32_16x16x32_bf16 v[70:73], v[166:169], v[220:223], v[70:73]
	s_setprio 0
	s_setprio 1
	v_mfma_f32_16x16x32_bf16 v[122:125], v[170:173], v[188:191], v[122:125]
	v_mfma_f32_16x16x32_bf16 v[122:125], v[174:177], v[196:199], v[122:125]
	v_mfma_f32_16x16x32_bf16 v[106:109], v[170:173], v[200:203], v[106:109]
	v_mfma_f32_16x16x32_bf16 v[106:109], v[174:177], v[204:207], v[106:109]
	v_mfma_f32_16x16x32_bf16 v[90:93], v[170:173], v[208:211], v[90:93]
	v_mfma_f32_16x16x32_bf16 v[90:93], v[174:177], v[212:215], v[90:93]
	v_mfma_f32_16x16x32_bf16 v[74:77], v[170:173], v[216:219], v[74:77]
	v_mfma_f32_16x16x32_bf16 v[74:77], v[174:177], v[220:223], v[74:77]
	v_mfma_f32_16x16x32_bf16 v[114:117], v[180:183], v[188:191], v[114:117]
	v_mfma_f32_16x16x32_bf16 v[114:117], v[184:187], v[196:199], v[114:117]
	v_mfma_f32_16x16x32_bf16 v[98:101], v[180:183], v[200:203], v[98:101]
	v_mfma_f32_16x16x32_bf16 v[98:101], v[184:187], v[204:207], v[98:101]
	v_mfma_f32_16x16x32_bf16 v[82:85], v[180:183], v[208:211], v[82:85]
	v_mfma_f32_16x16x32_bf16 v[82:85], v[184:187], v[212:215], v[82:85]
	v_mfma_f32_16x16x32_bf16 v[66:69], v[180:183], v[216:219], v[66:69]
	v_mfma_f32_16x16x32_bf16 v[66:69], v[184:187], v[220:223], v[66:69]
	s_setprio 0
	s_barrier
	s_add_u32 s74, s72, 0x8000
	s_addc_u32 s75, s73, 0
	s_add_i32 s77, s77, s3
	v_lshl_add_u64 v[224:225], s[74:75], 0, v[132:133]
	s_mov_b32 m0, s77
	ds_read_b128 v[188:191], v152 offset:49152
	ds_read_b128 v[196:199], v152 offset:50176
	ds_read_b128 v[200:203], v152 offset:51200
	ds_read_b128 v[204:207], v152 offset:52224
	ds_read_b128 v[208:211], v152 offset:53248
	ds_read_b128 v[212:215], v152 offset:54272
	ds_read_b128 v[216:219], v152 offset:55296
	ds_read_b128 v[220:223], v152 offset:56320
	global_load_lds_dwordx4 v[224:225], off
	s_add_i32 m0, s77, 0x2000
	s_add_u32 s72, s72, 0xc000
	v_lshl_add_u64 v[224:225], s[74:75], 0, v[136:137]
	s_addc_u32 s73, s73, 0
	s_add_i32 s74, s78, s3
	global_load_lds_dwordx4 v[224:225], off
	v_lshl_add_u64 v[224:225], s[72:73], 0, v[132:133]
	s_mov_b32 m0, s74
	s_nop 0
	global_load_lds_dwordx4 v[224:225], off
	v_lshl_add_u64 v[224:225], s[72:73], 0, v[136:137]
	s_add_i32 m0, s74, 0x2000
	s_nop 0
	global_load_lds_dwordx4 v[224:225], off
	s_waitcnt vmcnt(6)
	s_waitcnt lgkmcnt(0)
	s_barrier
	s_setprio 1
	s_waitcnt lgkmcnt(0)
	v_mfma_f32_16x16x32_bf16 v[62:65], v[154:157], v[188:191], v[62:65]
	v_mfma_f32_16x16x32_bf16 v[62:65], v[158:161], v[196:199], v[62:65]
	v_mfma_f32_16x16x32_bf16 v[46:49], v[154:157], v[200:203], v[46:49]
	v_mfma_f32_16x16x32_bf16 v[46:49], v[158:161], v[204:207], v[46:49]
	v_mfma_f32_16x16x32_bf16 v[30:33], v[154:157], v[208:211], v[30:33]
	v_mfma_f32_16x16x32_bf16 v[30:33], v[158:161], v[212:215], v[30:33]
	v_mfma_f32_16x16x32_bf16 v[14:17], v[154:157], v[216:219], v[14:17]
	v_mfma_f32_16x16x32_bf16 v[14:17], v[158:161], v[220:223], v[14:17]
	v_mfma_f32_16x16x32_bf16 v[54:57], v[162:165], v[188:191], v[54:57]
	v_mfma_f32_16x16x32_bf16 v[54:57], v[166:169], v[196:199], v[54:57]
	v_mfma_f32_16x16x32_bf16 v[38:41], v[162:165], v[200:203], v[38:41]
	v_mfma_f32_16x16x32_bf16 v[38:41], v[166:169], v[204:207], v[38:41]
	v_mfma_f32_16x16x32_bf16 v[22:25], v[162:165], v[208:211], v[22:25]
	v_mfma_f32_16x16x32_bf16 v[22:25], v[166:169], v[212:215], v[22:25]
	v_mfma_f32_16x16x32_bf16 v[6:9], v[162:165], v[216:219], v[6:9]
	v_mfma_f32_16x16x32_bf16 v[6:9], v[166:169], v[220:223], v[6:9]
	s_setprio 0
	s_setprio 1
	v_mfma_f32_16x16x32_bf16 v[58:61], v[170:173], v[188:191], v[58:61]
	v_mfma_f32_16x16x32_bf16 v[58:61], v[174:177], v[196:199], v[58:61]
	v_mfma_f32_16x16x32_bf16 v[42:45], v[170:173], v[200:203], v[42:45]
	v_mfma_f32_16x16x32_bf16 v[42:45], v[174:177], v[204:207], v[42:45]
	v_mfma_f32_16x16x32_bf16 v[26:29], v[170:173], v[208:211], v[26:29]
	v_mfma_f32_16x16x32_bf16 v[26:29], v[174:177], v[212:215], v[26:29]
	v_mfma_f32_16x16x32_bf16 v[10:13], v[170:173], v[216:219], v[10:13]
	v_mfma_f32_16x16x32_bf16 v[10:13], v[174:177], v[220:223], v[10:13]
	v_mfma_f32_16x16x32_bf16 v[50:53], v[180:183], v[188:191], v[50:53]
	v_mfma_f32_16x16x32_bf16 v[50:53], v[184:187], v[196:199], v[50:53]
	v_mfma_f32_16x16x32_bf16 v[34:37], v[180:183], v[200:203], v[34:37]
	v_mfma_f32_16x16x32_bf16 v[34:37], v[184:187], v[204:207], v[34:37]
	v_mfma_f32_16x16x32_bf16 v[18:21], v[180:183], v[208:211], v[18:21]
	v_mfma_f32_16x16x32_bf16 v[18:21], v[184:187], v[212:215], v[18:21]
	v_mfma_f32_16x16x32_bf16 v[2:5], v[180:183], v[216:219], v[2:5]
	v_mfma_f32_16x16x32_bf16 v[2:5], v[184:187], v[220:223], v[2:5]
	s_setprio 0
	s_barrier
	s_add_i32 s76, s76, 2
	s_add_u32 s48, s48, 0x10000
	s_addc_u32 s49, s49, 0
	s_add_u32 s68, s68, 0x10000
	s_addc_u32 s69, s69, 0
	s_cmp_gt_u32 s76, 61
	s_cbranch_scc0 .LBB0_115
	s_and_b64 vcc, exec, s[14:15]
	s_cbranch_vccz .LBB0_118
	s_barrier

; #define PG8_STAGE(bufoff, gbase, voff) do { _Pragma("unroll") for (int _i = 0; _i < 2; ++_i) \
;         __builtin_amdgcn_global_load_lds((const unsigned*)((const char*)(gbase) + (voff)[_i]), (PG8_LAS unsigned*)(lds + (bufoff) + ldsw + _i * 8192), 16, 0, 0); } while (0)
; #define PG8_LDA(dst, b, h) do { _Pragma("unroll") for (int m = 0; m < 4; ++m) _Pragma("unroll") for (int k = 0; k < 2; ++k) dst[m][k] = *(const PG8_LAS bf16x8*)(lds + PG8_SA(b, h) + aoff + m * 2048 + k * 1024); } while (0)
; #define PG8_LDB(dst, b, h) do { _Pragma("unroll") for (int n = 0; n < 2; ++n) _Pragma("unroll") for (int k = 0; k < 2; ++k) dst[n][k] = *(const PG8_LAS bf16x8*)(lds + PG8_SB(b, h) + boff + n * 2048 + k * 1024); } while (0)
; #define PG8_WAIT_V(n) asm volatile("s_waitcnt vmcnt(" #n ")" ::: "memory")
; template <class Epi, class Sched, bool ALIGN_EPI = false, bool SP2 = false>
; __device__ __forceinline__ void gemm_phase(PG8_LAS unsigned char* lds, const Gemm g, const Sched& S, const Epi& E) {
;     ...
;             const char* a1 = cA + (size_t)(t + 1) * kstep;
;             const char* a2 = last ? nA : cA + (size_t)(t + 2) * kstep; const char* b2 = last ? nB : cB + (size_t)(t + 2) * kstep;
;             const char* a3 = a2 + kstep; const char* b3 = b2 + kstep;
;             if (last && has_next) S.a_ready(nxt);
;             if constexpr (SP2) {
;             PG8_LDB(B0, 0, 0); PG8_LDB(B1, 0, 1); PG8_SCHED; PG8_LDA(At, 0, 0); PG8_STAGE(PG8_SA(1, 1), a1 + hstep, voffA);
;             PG8_WAIT_V(8); PG8_WAIT_L(0); PG8_BAR; PG8_MMA(0, 0, At, B0); PG8_MMA(0, 1, At, B1); PG8_BAR; PG8_SCHED;
;             PG8_LDA(At, 0, 1); PG8_STAGE(PG8_SB(0, 0), b2, voffB); PG8_STAGE(PG8_SB(0, 1), b2 + hstep, voffB); PG8_STAGE(PG8_SA(0, 0), a2, voffA);
;             PG8_WAIT_V(8); PG8_WAIT_L(0); PG8_BAR; PG8_MMA(1, 0, At, B0); PG8_MMA(1, 1, At, B1); PG8_BAR; PG8_SCHED;
;             PG8_LDB(B0, 1, 0); PG8_LDB(B1, 1, 1); PG8_SCHED; PG8_LDA(At, 1, 0); PG8_STAGE(PG8_SA(0, 1), a2 + hstep, voffA);
;             PG8_WAIT_V(8); PG8_WAIT_L(0); PG8_BAR; PG8_MMA(0, 0, At, B0); PG8_MMA(0, 1, At, B1); PG8_BAR; PG8_SCHED;
;             PG8_LDA(At, 1, 1); PG8_STAGE(PG8_SB(1, 0), b3, voffB); PG8_STAGE(PG8_SB(1, 1), b3 + hstep, voffB); PG8_STAGE(PG8_SA(1, 0), a3, voffA);
;             PG8_WAIT_V(8); PG8_WAIT_L(0); PG8_BAR; PG8_MMA(1, 0, At, B0); PG8_MMA(1, 1, At, B1); PG8_BAR; PG8_SCHED;
.LBB0_200:
	ds_read_b128 v[148:151], v154
	ds_read_b128 v[158:161], v154 offset:1024
	ds_read_b128 v[162:165], v154 offset:2048
	ds_read_b128 v[166:169], v154 offset:3072
	ds_read_b128 v[170:173], v155
	ds_read_b128 v[174:177], v155 offset:1024
	ds_read_b128 v[180:183], v155 offset:2048
	ds_read_b128 v[184:187], v155 offset:3072
	s_add_u32 s46, s44, 0x4000
	s_addc_u32 s47, s45, 0
	s_cmpk_eq_i32 s76, 0xa8
	s_cselect_b32 s50, s6, s46
	s_cselect_b32 s51, s7, s47
	s_cselect_b32 s48, s24, s74
	s_cselect_b32 s49, s25, s75
	s_add_u32 s46, s50, 0x8000
	s_addc_u32 s47, s51, 0
	s_sub_u32 s46, s44, 0x4000
	s_subb_u32 s47, s45, 0
	v_lshl_add_u64 v[224:225], s[46:47], 0, v[130:131]
	s_mov_b32 m0, s57
	s_nop 0
	global_load_lds_dwordx4 v[224:225], off
	v_lshl_add_u64 v[224:225], s[46:47], 0, v[134:135]
	s_mov_b32 m0, s58
	s_nop 0
	global_load_lds_dwordx4 v[224:225], off
	v_lshl_add_u64 v[224:225], s[44:45], 0, v[140:141]
	s_add_i32 m0, s26, 0xc000
	ds_read_b128 v[188:191], v156
	ds_read_b128 v[196:199], v156 offset:1024
	ds_read_b128 v[200:203], v156 offset:2048
	ds_read_b128 v[204:207], v156 offset:3072
	ds_read_b128 v[208:211], v156 offset:4096
	ds_read_b128 v[212:215], v156 offset:5120
	ds_read_b128 v[216:219], v156 offset:6144
	ds_read_b128 v[220:223], v156 offset:7168
	global_load_lds_dwordx4 v[224:225], off
	v_lshl_add_u64 v[224:225], s[44:45], 0, v[142:143]
	s_add_i32 m0, s26, 0xe000
	s_nop 0
	global_load_lds_dwordx4 v[224:225], off
	s_waitcnt vmcnt(8)
	s_waitcnt lgkmcnt(0)
	s_barrier
	s_setprio 1
	s_waitcnt lgkmcnt(0)
	v_mfma_f32_16x16x32_bf16 v[126:129], v[148:151], v[188:191], v[126:129]
	v_mfma_f32_16x16x32_bf16 v[126:129], v[158:161], v[196:199], v[126:129]
	v_mfma_f32_16x16x32_bf16 v[110:113], v[148:151], v[200:203], v[110:113]
	v_mfma_f32_16x16x32_bf16 v[110:113], v[158:161], v[204:207], v[110:113]
	v_mfma_f32_16x16x32_bf16 v[94:97], v[148:151], v[208:211], v[94:97]
	v_mfma_f32_16x16x32_bf16 v[94:97], v[158:161], v[212:215], v[94:97]
	v_mfma_f32_16x16x32_bf16 v[78:81], v[148:151], v[216:219], v[78:81]
	v_mfma_f32_16x16x32_bf16 v[78:81], v[158:161], v[220:223], v[78:81]
	v_mfma_f32_16x16x32_bf16 v[122:125], v[162:165], v[188:191], v[122:125]
	v_mfma_f32_16x16x32_bf16 v[122:125], v[166:169], v[196:199], v[122:125]
	v_mfma_f32_16x16x32_bf16 v[106:109], v[162:165], v[200:203], v[106:109]
	v_mfma_f32_16x16x32_bf16 v[106:109], v[166:169], v[204:207], v[106:109]
	v_mfma_f32_16x16x32_bf16 v[90:93], v[162:165], v[208:211], v[90:93]
	v_mfma_f32_16x16x32_bf16 v[90:93], v[166:169], v[212:215], v[90:93]
	v_mfma_f32_16x16x32_bf16 v[74:77], v[162:165], v[216:219], v[74:77]
	v_mfma_f32_16x16x32_bf16 v[74:77], v[166:169], v[220:223], v[74:77]
	s_setprio 0
	s_setprio 1
	v_mfma_f32_16x16x32_bf16 v[118:121], v[170:173], v[188:191], v[118:121]
	v_mfma_f32_16x16x32_bf16 v[118:121], v[174:177], v[196:199], v[118:121]
	v_mfma_f32_16x16x32_bf16 v[102:105], v[170:173], v[200:203], v[102:105]
	v_mfma_f32_16x16x32_bf16 v[102:105], v[174:177], v[204:207], v[102:105]
	v_mfma_f32_16x16x32_bf16 v[86:89], v[170:173], v[208:211], v[86:89]
	v_mfma_f32_16x16x32_bf16 v[86:89], v[174:177], v[212:215], v[86:89]
	v_mfma_f32_16x16x32_bf16 v[70:73], v[170:173], v[216:219], v[70:73]
	v_mfma_f32_16x16x32_bf16 v[70:73], v[174:177], v[220:223], v[70:73]
	v_mfma_f32_16x16x32_bf16 v[114:117], v[180:183], v[188:191], v[114:117]
	v_mfma_f32_16x16x32_bf16 v[114:117], v[184:187], v[196:199], v[114:117]
	v_mfma_f32_16x16x32_bf16 v[98:101], v[180:183], v[200:203], v[98:101]
	v_mfma_f32_16x16x32_bf16 v[98:101], v[184:187], v[204:207], v[98:101]
	v_mfma_f32_16x16x32_bf16 v[82:85], v[180:183], v[208:211], v[82:85]
	v_mfma_f32_16x16x32_bf16 v[82:85], v[184:187], v[212:215], v[82:85]
	v_mfma_f32_16x16x32_bf16 v[66:69], v[180:183], v[216:219], v[66:69]
	v_mfma_f32_16x16x32_bf16 v[66:69], v[184:187], v[220:223], v[66:69]
	s_setprio 0
	s_barrier
	s_add_i32 s77, s59, s3
	v_lshl_add_u64 v[224:225], s[48:49], 0, v[132:133]
	s_mov_b32 m0, s77
	ds_read_b128 v[188:191], v156 offset:16384
	ds_read_b128 v[196:199], v156 offset:17408
	ds_read_b128 v[200:203], v156 offset:18432
	ds_read_b128 v[204:207], v156 offset:19456
	ds_read_b128 v[208:211], v156 offset:20480
	ds_read_b128 v[212:215], v156 offset:21504
	ds_read_b128 v[216:219], v156 offset:22528
	ds_read_b128 v[220:223], v156 offset:23552
	global_load_lds_dwordx4 v[224:225], off
	s_add_i32 m0, s77, 0x2000
	s_add_u32 s78, s48, 0x4000
	v_lshl_add_u64 v[224:225], s[48:49], 0, v[136:137]
	s_addc_u32 s79, s49, 0
	s_add_i32 s77, s61, s3
	global_load_lds_dwordx4 v[224:225], off
	v_lshl_add_u64 v[224:225], s[78:79], 0, v[132:133]
	s_mov_b32 m0, s77
	s_nop 0
	global_load_lds_dwordx4 v[224:225], off
	v_lshl_add_u64 v[224:225], s[78:79], 0, v[136:137]
	s_add_i32 m0, s77, 0x2000
	s_nop 0
	global_load_lds_dwordx4 v[224:225], off
	s_waitcnt vmcnt(6)
	s_waitcnt lgkmcnt(0)
	s_barrier
; #define PG8_STAGE(bufoff, gbase, voff) do { _Pragma("unroll") for (int _i = 0; _i < 2; ++_i) \
;         __builtin_amdgcn_global_load_lds((const unsigned*)((const char*)(gbase) + (voff)[_i]), (PG8_LAS unsigned*)(lds + (bufoff) + ldsw + _i * 8192), 16, 0, 0); } while (0)
; #define PG8_LDA(dst, b, h) do { _Pragma("unroll") for (int m = 0; m < 4; ++m) _Pragma("unroll") for (int k = 0; k < 2; ++k) dst[m][k] = *(const PG8_LAS bf16x8*)(lds + PG8_SA(b, h) + aoff + m * 2048 + k * 1024); } while (0)
; #define PG8_LDB(dst, b, h) do { _Pragma("unroll") for (int n = 0; n < 2; ++n) _Pragma("unroll") for (int k = 0; k < 2; ++k) dst[n][k] = *(const PG8_LAS bf16x8*)(lds + PG8_SB(b, h) + boff + n * 2048 + k * 1024); } while (0)
; #define PG8_MMA(ai, bj, At, Bt) do { __builtin_amdgcn_s_setprio(1); _Pragma("unroll") for (int m = 0; m < 4; ++m) _Pragma("unroll") for (int n = 0; n < 2; ++n) _Pragma("unroll") for (int k = 0; k < 2; ++k) \
;         acc[ai][bj][m][n] = __builtin_amdgcn_mfma_f32_16x16x32_bf16(Bt[n][k], At[m][k], acc[ai][bj][m][n], 0, 0, 0); __builtin_amdgcn_s_setprio(0); } while (0)
; #define PG8_BAR __builtin_amdgcn_s_barrier()
; template <class Epi, class Sched, bool ALIGN_EPI = false, bool SP2 = false>
; __device__ __forceinline__ void gemm_phase(PG8_LAS unsigned char* lds, const Gemm g, const Sched& S, const Epi& E) {
;     ...
;             if constexpr (SP2) {
;             PG8_LDB(B0, 0, 0); PG8_LDB(B1, 0, 1); PG8_SCHED; PG8_LDA(At, 0, 0); PG8_STAGE(PG8_SA(1, 1), a1 + hstep, voffA);
;             PG8_WAIT_V(8); PG8_WAIT_L(0); PG8_BAR; PG8_MMA(0, 0, At, B0); PG8_MMA(0, 1, At, B1); PG8_BAR; PG8_SCHED;
;             PG8_LDA(At, 0, 1); PG8_STAGE(PG8_SB(0, 0), b2, voffB); PG8_STAGE(PG8_SB(0, 1), b2 + hstep, voffB); PG8_STAGE(PG8_SA(0, 0), a2, voffA);
;             PG8_WAIT_V(8); PG8_WAIT_L(0); PG8_BAR; PG8_MMA(1, 0, At, B0); PG8_MMA(1, 1, At, B1); PG8_BAR; PG8_SCHED;
;             PG8_LDB(B0, 1, 0); PG8_LDB(B1, 1, 1); PG8_SCHED; PG8_LDA(At, 1, 0); PG8_STAGE(PG8_SA(0, 1), a2 + hstep, voffA);
;             PG8_WAIT_V(8); PG8_WAIT_L(0); PG8_BAR; PG8_MMA(0, 0, At, B0); PG8_MMA(0, 1, At, B1); PG8_BAR; PG8_SCHED;
;             PG8_LDA(At, 1, 1); PG8_STAGE(PG8_SB(1, 0), b3, voffB); PG8_STAGE(PG8_SB(1, 1), b3 + hstep, voffB); PG8_STAGE(PG8_SA(1, 0), a3, voffA);
;             PG8_WAIT_V(8); PG8_WAIT_L(0); PG8_BAR; PG8_MMA(1, 0, At, B0); PG8_MMA(1, 1, At, B1); PG8_BAR; PG8_SCHED;
	s_setprio 1
	s_waitcnt lgkmcnt(0)
	v_mfma_f32_16x16x32_bf16 v[62:65], v[148:151], v[188:191], v[62:65]
	v_mfma_f32_16x16x32_bf16 v[62:65], v[158:161], v[196:199], v[62:65]
	v_mfma_f32_16x16x32_bf16 v[46:49], v[148:151], v[200:203], v[46:49]
	v_mfma_f32_16x16x32_bf16 v[46:49], v[158:161], v[204:207], v[46:49]
	v_mfma_f32_16x16x32_bf16 v[30:33], v[148:151], v[208:211], v[30:33]
	v_mfma_f32_16x16x32_bf16 v[30:33], v[158:161], v[212:215], v[30:33]
	v_mfma_f32_16x16x32_bf16 v[14:17], v[148:151], v[216:219], v[14:17]
	v_mfma_f32_16x16x32_bf16 v[14:17], v[158:161], v[220:223], v[14:17]
	v_mfma_f32_16x16x32_bf16 v[58:61], v[162:165], v[188:191], v[58:61]
	v_mfma_f32_16x16x32_bf16 v[58:61], v[166:169], v[196:199], v[58:61]
	v_mfma_f32_16x16x32_bf16 v[42:45], v[162:165], v[200:203], v[42:45]
	v_mfma_f32_16x16x32_bf16 v[42:45], v[166:169], v[204:207], v[42:45]
	v_mfma_f32_16x16x32_bf16 v[26:29], v[162:165], v[208:211], v[26:29]
	v_mfma_f32_16x16x32_bf16 v[26:29], v[166:169], v[212:215], v[26:29]
	v_mfma_f32_16x16x32_bf16 v[10:13], v[162:165], v[216:219], v[10:13]
	v_mfma_f32_16x16x32_bf16 v[10:13], v[166:169], v[220:223], v[10:13]
	s_setprio 0
	s_setprio 1
	v_mfma_f32_16x16x32_bf16 v[54:57], v[170:173], v[188:191], v[54:57]
	v_mfma_f32_16x16x32_bf16 v[54:57], v[174:177], v[196:199], v[54:57]
	v_mfma_f32_16x16x32_bf16 v[38:41], v[170:173], v[200:203], v[38:41]
	v_mfma_f32_16x16x32_bf16 v[38:41], v[174:177], v[204:207], v[38:41]
	v_mfma_f32_16x16x32_bf16 v[22:25], v[170:173], v[208:211], v[22:25]
	v_mfma_f32_16x16x32_bf16 v[22:25], v[174:177], v[212:215], v[22:25]
	v_mfma_f32_16x16x32_bf16 v[6:9], v[170:173], v[216:219], v[6:9]
	v_mfma_f32_16x16x32_bf16 v[6:9], v[174:177], v[220:223], v[6:9]
	v_mfma_f32_16x16x32_bf16 v[50:53], v[180:183], v[188:191], v[50:53]
	v_mfma_f32_16x16x32_bf16 v[50:53], v[184:187], v[196:199], v[50:53]
	v_mfma_f32_16x16x32_bf16 v[34:37], v[180:183], v[200:203], v[34:37]
	v_mfma_f32_16x16x32_bf16 v[34:37], v[184:187], v[204:207], v[34:37]
	v_mfma_f32_16x16x32_bf16 v[18:21], v[180:183], v[208:211], v[18:21]
	v_mfma_f32_16x16x32_bf16 v[18:21], v[184:187], v[212:215], v[18:21]
	v_mfma_f32_16x16x32_bf16 v[2:5], v[180:183], v[216:219], v[2:5]
	v_mfma_f32_16x16x32_bf16 v[2:5], v[184:187], v[220:223], v[2:5]
	s_setprio 0
	s_barrier
	s_add_i32 s77, 0, 0x18000
	v_add_u32_e32 v138, s77, v153
	s_add_i32 s78, 0, 0x1c000
	ds_read_b128 v[148:151], v138
	ds_read_b128 v[158:161], v138 offset:1024
	ds_read_b128 v[162:165], v138 offset:2048
	ds_read_b128 v[166:169], v138 offset:3072
	v_add_u32_e32 v138, s78, v153
	ds_read_b128 v[170:173], v138
	ds_read_b128 v[174:177], v138 offset:1024
	ds_read_b128 v[180:183], v138 offset:2048
	ds_read_b128 v[184:187], v138 offset:3072
	v_lshl_add_u64 v[224:225], s[50:51], 0, v[130:131]
	s_mov_b32 m0, s26
	s_nop 0
	global_load_lds_dwordx4 v[224:225], off
	v_lshl_add_u64 v[224:225], s[50:51], 0, v[134:135]
	s_mov_b32 m0, s27
	s_nop 0
	global_load_lds_dwordx4 v[224:225], off
	s_add_u32 s50, s50, 0x4000
	s_addc_u32 s51, s51, 0
	s_mov_b32 m0, s28
	v_lshl_add_u64 v[224:225], s[50:51], 0, v[130:131]
	ds_read_b128 v[188:191], v156 offset:32768
	ds_read_b128 v[196:199], v156 offset:33792
	ds_read_b128 v[200:203], v156 offset:34816
	ds_read_b128 v[204:207], v156 offset:35840
	ds_read_b128 v[208:211], v156 offset:36864
	ds_read_b128 v[212:215], v156 offset:37888
	ds_read_b128 v[216:219], v156 offset:38912
	ds_read_b128 v[220:223], v156 offset:39936
	global_load_lds_dwordx4 v[224:225], off
	v_lshl_add_u64 v[224:225], s[50:51], 0, v[134:135]
	s_mov_b32 m0, s29
	s_nop 0
	global_load_lds_dwordx4 v[224:225], off
	s_waitcnt vmcnt(8)
	s_waitcnt lgkmcnt(0)
	s_barrier
; #define PG8_STAGE(bufoff, gbase, voff) do { _Pragma("unroll") for (int _i = 0; _i < 2; ++_i) \
;         __builtin_amdgcn_global_load_lds((const unsigned*)((const char*)(gbase) + (voff)[_i]), (PG8_LAS unsigned*)(lds + (bufoff) + ldsw + _i * 8192), 16, 0, 0); } while (0)
; #define PG8_LDA(dst, b, h) do { _Pragma("unroll") for (int m = 0; m < 4; ++m) _Pragma("unroll") for (int k = 0; k < 2; ++k) dst[m][k] = *(const PG8_LAS bf16x8*)(lds + PG8_SA(b, h) + aoff + m * 2048 + k * 1024); } while (0)
; #define PG8_LDB(dst, b, h) do { _Pragma("unroll") for (int n = 0; n < 2; ++n) _Pragma("unroll") for (int k = 0; k < 2; ++k) dst[n][k] = *(const PG8_LAS bf16x8*)(lds + PG8_SB(b, h) + boff + n * 2048 + k * 1024); } while (0)
; #define PG8_MMA(ai, bj, At, Bt) do { __builtin_amdgcn_s_setprio(1); _Pragma("unroll") for (int m = 0; m < 4; ++m) _Pragma("unroll") for (int n = 0; n < 2; ++n) _Pragma("unroll") for (int k = 0; k < 2; ++k) \
;         acc[ai][bj][m][n] = __builtin_amdgcn_mfma_f32_16x16x32_bf16(Bt[n][k], At[m][k], acc[ai][bj][m][n], 0, 0, 0); __builtin_amdgcn_s_setprio(0); } while (0)
; #define PG8_BAR __builtin_amdgcn_s_barrier()
; template <class Epi, class Sched, bool ALIGN_EPI = false, bool SP2 = false>
; __device__ __forceinline__ void gemm_phase(PG8_LAS unsigned char* lds, const Gemm g, const Sched& S, const Epi& E) {
;     ...
;             if constexpr (SP2) {
;             PG8_LDB(B0, 0, 0); PG8_LDB(B1, 0, 1); PG8_SCHED; PG8_LDA(At, 0, 0); PG8_STAGE(PG8_SA(1, 1), a1 + hstep, voffA);
;             PG8_WAIT_V(8); PG8_WAIT_L(0); PG8_BAR; PG8_MMA(0, 0, At, B0); PG8_MMA(0, 1, At, B1); PG8_BAR; PG8_SCHED;
;             PG8_LDA(At, 0, 1); PG8_STAGE(PG8_SB(0, 0), b2, voffB); PG8_STAGE(PG8_SB(0, 1), b2 + hstep, voffB); PG8_STAGE(PG8_SA(0, 0), a2, voffA);
;             PG8_WAIT_V(8); PG8_WAIT_L(0); PG8_BAR; PG8_MMA(1, 0, At, B0); PG8_MMA(1, 1, At, B1); PG8_BAR; PG8_SCHED;
;             PG8_LDB(B0, 1, 0); PG8_LDB(B1, 1, 1); PG8_SCHED; PG8_LDA(At, 1, 0); PG8_STAGE(PG8_SA(0, 1), a2 + hstep, voffA);
;             PG8_WAIT_V(8); PG8_WAIT_L(0); PG8_BAR; PG8_MMA(0, 0, At, B0); PG8_MMA(0, 1, At, B1); PG8_BAR; PG8_SCHED;
;             PG8_LDA(At, 1, 1); PG8_STAGE(PG8_SB(1, 0), b3, voffB); PG8_STAGE(PG8_SB(1, 1), b3 + hstep, voffB); PG8_STAGE(PG8_SA(1, 0), a3, voffA);
;             PG8_WAIT_V(8); PG8_WAIT_L(0); PG8_BAR; PG8_MMA(1, 0, At, B0); PG8_MMA(1, 1, At, B1); PG8_BAR; PG8_SCHED;
	s_setprio 1
	s_waitcnt lgkmcnt(0)
	v_mfma_f32_16x16x32_bf16 v[126:129], v[148:151], v[188:191], v[126:129]
	v_mfma_f32_16x16x32_bf16 v[126:129], v[158:161], v[196:199], v[126:129]
	v_mfma_f32_16x16x32_bf16 v[110:113], v[148:151], v[200:203], v[110:113]
	v_mfma_f32_16x16x32_bf16 v[110:113], v[158:161], v[204:207], v[110:113]
	v_mfma_f32_16x16x32_bf16 v[94:97], v[148:151], v[208:211], v[94:97]
	v_mfma_f32_16x16x32_bf16 v[94:97], v[158:161], v[212:215], v[94:97]
	v_mfma_f32_16x16x32_bf16 v[78:81], v[148:151], v[216:219], v[78:81]
	v_mfma_f32_16x16x32_bf16 v[78:81], v[158:161], v[220:223], v[78:81]
	v_mfma_f32_16x16x32_bf16 v[122:125], v[162:165], v[188:191], v[122:125]
	v_mfma_f32_16x16x32_bf16 v[122:125], v[166:169], v[196:199], v[122:125]
	v_mfma_f32_16x16x32_bf16 v[106:109], v[162:165], v[200:203], v[106:109]
	v_mfma_f32_16x16x32_bf16 v[106:109], v[166:169], v[204:207], v[106:109]
	v_mfma_f32_16x16x32_bf16 v[90:93], v[162:165], v[208:211], v[90:93]
	v_mfma_f32_16x16x32_bf16 v[90:93], v[166:169], v[212:215], v[90:93]
	v_mfma_f32_16x16x32_bf16 v[74:77], v[162:165], v[216:219], v[74:77]
	v_mfma_f32_16x16x32_bf16 v[74:77], v[166:169], v[220:223], v[74:77]
	s_setprio 0
	s_setprio 1
	v_mfma_f32_16x16x32_bf16 v[118:121], v[170:173], v[188:191], v[118:121]
	v_mfma_f32_16x16x32_bf16 v[118:121], v[174:177], v[196:199], v[118:121]
	v_mfma_f32_16x16x32_bf16 v[102:105], v[170:173], v[200:203], v[102:105]
	v_mfma_f32_16x16x32_bf16 v[102:105], v[174:177], v[204:207], v[102:105]
	v_mfma_f32_16x16x32_bf16 v[86:89], v[170:173], v[208:211], v[86:89]
	v_mfma_f32_16x16x32_bf16 v[86:89], v[174:177], v[212:215], v[86:89]
	v_mfma_f32_16x16x32_bf16 v[70:73], v[170:173], v[216:219], v[70:73]
	v_mfma_f32_16x16x32_bf16 v[70:73], v[174:177], v[220:223], v[70:73]
	v_mfma_f32_16x16x32_bf16 v[114:117], v[180:183], v[188:191], v[114:117]
	v_mfma_f32_16x16x32_bf16 v[114:117], v[184:187], v[196:199], v[114:117]
	v_mfma_f32_16x16x32_bf16 v[98:101], v[180:183], v[200:203], v[98:101]
	v_mfma_f32_16x16x32_bf16 v[98:101], v[184:187], v[204:207], v[98:101]
	v_mfma_f32_16x16x32_bf16 v[82:85], v[180:183], v[208:211], v[82:85]
	v_mfma_f32_16x16x32_bf16 v[82:85], v[184:187], v[212:215], v[82:85]
	v_mfma_f32_16x16x32_bf16 v[66:69], v[180:183], v[216:219], v[66:69]
	v_mfma_f32_16x16x32_bf16 v[66:69], v[184:187], v[220:223], v[66:69]
	s_setprio 0
	s_barrier
	s_add_u32 s50, s48, 0x8000
	s_addc_u32 s51, s49, 0
	s_add_i32 s77, s77, s3
	v_lshl_add_u64 v[224:225], s[50:51], 0, v[132:133]
	s_mov_b32 m0, s77
	ds_read_b128 v[188:191], v156 offset:49152
	ds_read_b128 v[196:199], v156 offset:50176
	ds_read_b128 v[200:203], v156 offset:51200
	ds_read_b128 v[204:207], v156 offset:52224
	ds_read_b128 v[208:211], v156 offset:53248
	ds_read_b128 v[212:215], v156 offset:54272
	ds_read_b128 v[216:219], v156 offset:55296
	ds_read_b128 v[220:223], v156 offset:56320
	global_load_lds_dwordx4 v[224:225], off
	s_add_i32 m0, s77, 0x2000
	s_add_u32 s48, s48, 0xc000
	v_lshl_add_u64 v[224:225], s[50:51], 0, v[136:137]
	s_addc_u32 s49, s49, 0
	s_add_i32 s50, s78, s3
	global_load_lds_dwordx4 v[224:225], off
	v_lshl_add_u64 v[224:225], s[48:49], 0, v[132:133]
	s_mov_b32 m0, s50
	s_nop 0
	global_load_lds_dwordx4 v[224:225], off
	v_lshl_add_u64 v[224:225], s[48:49], 0, v[136:137]
	s_add_i32 m0, s50, 0x2000
	s_nop 0
	global_load_lds_dwordx4 v[224:225], off
	s_waitcnt vmcnt(6)
	s_waitcnt lgkmcnt(0)
	s_barrier
	s_setprio 1
	s_waitcnt lgkmcnt(0)
	v_mfma_f32_16x16x32_bf16 v[62:65], v[148:151], v[188:191], v[62:65]
	v_mfma_f32_16x16x32_bf16 v[62:65], v[158:161], v[196:199], v[62:65]
	v_mfma_f32_16x16x32_bf16 v[46:49], v[148:151], v[200:203], v[46:49]
	v_mfma_f32_16x16x32_bf16 v[46:49], v[158:161], v[204:207], v[46:49]
	v_mfma_f32_16x16x32_bf16 v[30:33], v[148:151], v[208:211], v[30:33]
	v_mfma_f32_16x16x32_bf16 v[30:33], v[158:161], v[212:215], v[30:33]
	v_mfma_f32_16x16x32_bf16 v[14:17], v[148:151], v[216:219], v[14:17]
	v_mfma_f32_16x16x32_bf16 v[14:17], v[158:161], v[220:223], v[14:17]
	v_mfma_f32_16x16x32_bf16 v[58:61], v[162:165], v[188:191], v[58:61]
	v_mfma_f32_16x16x32_bf16 v[58:61], v[166:169], v[196:199], v[58:61]
	v_mfma_f32_16x16x32_bf16 v[42:45], v[162:165], v[200:203], v[42:45]
	v_mfma_f32_16x16x32_bf16 v[42:45], v[166:169], v[204:207], v[42:45]
	v_mfma_f32_16x16x32_bf16 v[26:29], v[162:165], v[208:211], v[26:29]
	v_mfma_f32_16x16x32_bf16 v[26:29], v[166:169], v[212:215], v[26:29]
	v_mfma_f32_16x16x32_bf16 v[10:13], v[162:165], v[216:219], v[10:13]
	v_mfma_f32_16x16x32_bf16 v[10:13], v[166:169], v[220:223], v[10:13]
	s_setprio 0
	s_setprio 1
	v_mfma_f32_16x16x32_bf16 v[54:57], v[170:173], v[188:191], v[54:57]
	v_mfma_f32_16x16x32_bf16 v[54:57], v[174:177], v[196:199], v[54:57]
	v_mfma_f32_16x16x32_bf16 v[38:41], v[170:173], v[200:203], v[38:41]
	v_mfma_f32_16x16x32_bf16 v[38:41], v[174:177], v[204:207], v[38:41]
	v_mfma_f32_16x16x32_bf16 v[22:25], v[170:173], v[208:211], v[22:25]
	v_mfma_f32_16x16x32_bf16 v[22:25], v[174:177], v[212:215], v[22:25]
	v_mfma_f32_16x16x32_bf16 v[6:9], v[170:173], v[216:219], v[6:9]
	v_mfma_f32_16x16x32_bf16 v[6:9], v[174:177], v[220:223], v[6:9]
	v_mfma_f32_16x16x32_bf16 v[50:53], v[180:183], v[188:191], v[50:53]
	v_mfma_f32_16x16x32_bf16 v[50:53], v[184:187], v[196:199], v[50:53]
	v_mfma_f32_16x16x32_bf16 v[34:37], v[180:183], v[200:203], v[34:37]
	v_mfma_f32_16x16x32_bf16 v[34:37], v[184:187], v[204:207], v[34:37]
	v_mfma_f32_16x16x32_bf16 v[18:21], v[180:183], v[208:211], v[18:21]
	v_mfma_f32_16x16x32_bf16 v[18:21], v[184:187], v[212:215], v[18:21]
	v_mfma_f32_16x16x32_bf16 v[2:5], v[180:183], v[216:219], v[2:5]
	v_mfma_f32_16x16x32_bf16 v[2:5], v[184:187], v[220:223], v[2:5]
	s_setprio 0
	s_barrier
	s_add_i32 s76, s76, 2
	s_add_u32 s44, s44, 0x10000
	s_addc_u32 s45, s45, 0
	s_add_u32 s74, s74, 0x10000
	s_addc_u32 s75, s75, 0
	s_cmpk_gt_u32 s76, 0xa9
	s_cbranch_scc0 .LBB0_200
	s_and_b64 vcc, exec, s[18:19]
	s_cbranch_vccz .LBB0_203
	s_barrier

; #define PG8_STAGE(bufoff, gbase, voff) do { _Pragma("unroll") for (int _i = 0; _i < 2; ++_i) \
;         __builtin_amdgcn_global_load_lds((const unsigned*)((const char*)(gbase) + (voff)[_i]), (PG8_LAS unsigned*)(lds + (bufoff) + ldsw + _i * 8192), 16, 0, 0); } while (0)
; #define PG8_LDA(dst, b, h) do { _Pragma("unroll") for (int m = 0; m < 4; ++m) _Pragma("unroll") for (int k = 0; k < 2; ++k) dst[m][k] = *(const PG8_LAS bf16x8*)(lds + PG8_SA(b, h) + aoff + m * 2048 + k * 1024); } while (0)
; #define PG8_LDB(dst, b, h) do { _Pragma("unroll") for (int n = 0; n < 2; ++n) _Pragma("unroll") for (int k = 0; k < 2; ++k) dst[n][k] = *(const PG8_LAS bf16x8*)(lds + PG8_SB(b, h) + boff + n * 2048 + k * 1024); } while (0)
; #define PG8_WAIT_V(n) asm volatile("s_waitcnt vmcnt(" #n ")" ::: "memory")
; template <class Epi, class Sched, bool ALIGN_EPI = false, bool SP2 = false>
; __device__ __forceinline__ void gemm_phase(PG8_LAS unsigned char* lds, const Gemm g, const Sched& S, const Epi& E) {
;     ...
;             const char* a1 = cA + (size_t)(t + 1) * kstep;
;             const char* a2 = last ? nA : cA + (size_t)(t + 2) * kstep; const char* b2 = last ? nB : cB + (size_t)(t + 2) * kstep;
;             const char* a3 = a2 + kstep; const char* b3 = b2 + kstep;
;             if (last && has_next) S.a_ready(nxt);
;             if constexpr (SP2) {
;             PG8_LDB(B0, 0, 0); PG8_LDB(B1, 0, 1); PG8_SCHED; PG8_LDA(At, 0, 0); PG8_STAGE(PG8_SA(1, 1), a1 + hstep, voffA);
;             PG8_WAIT_V(8); PG8_WAIT_L(0); PG8_BAR; PG8_MMA(0, 0, At, B0); PG8_MMA(0, 1, At, B1); PG8_BAR; PG8_SCHED;
;             PG8_LDA(At, 0, 1); PG8_STAGE(PG8_SB(0, 0), b2, voffB); PG8_STAGE(PG8_SB(0, 1), b2 + hstep, voffB); PG8_STAGE(PG8_SA(0, 0), a2, voffA);
;             PG8_WAIT_V(8); PG8_WAIT_L(0); PG8_BAR; PG8_MMA(1, 0, At, B0); PG8_MMA(1, 1, At, B1); PG8_BAR; PG8_SCHED;
;             PG8_LDB(B0, 1, 0); PG8_LDB(B1, 1, 1); PG8_SCHED; PG8_LDA(At, 1, 0); PG8_STAGE(PG8_SA(0, 1), a2 + hstep, voffA);
;             PG8_WAIT_V(8); PG8_WAIT_L(0); PG8_BAR; PG8_MMA(0, 0, At, B0); PG8_MMA(0, 1, At, B1); PG8_BAR; PG8_SCHED;
;             PG8_LDA(At, 1, 1); PG8_STAGE(PG8_SB(1, 0), b3, voffB); PG8_STAGE(PG8_SB(1, 1), b3 + hstep, voffB); PG8_STAGE(PG8_SA(1, 0), a3, voffA);
;             PG8_WAIT_V(8); PG8_WAIT_L(0); PG8_BAR; PG8_MMA(1, 0, At, B0); PG8_MMA(1, 1, At, B1); PG8_BAR; PG8_SCHED;
.LBB0_290:
	ds_read_b128 v[146:149], v162
	ds_read_b128 v[150:153], v162 offset:1024
	ds_read_b128 v[154:157], v162 offset:2048
	ds_read_b128 v[168:171], v162 offset:3072
	ds_read_b128 v[172:175], v163
	ds_read_b128 v[180:183], v163 offset:1024
	ds_read_b128 v[184:187], v163 offset:2048
	ds_read_b128 v[188:191], v163 offset:3072
	s_add_u32 s59, s72, 0x4000
	s_addc_u32 s62, s73, 0
	s_cmp_eq_u32 s58, 60
	s_cselect_b32 s78, s19, s59
	s_cselect_b32 s79, s5, s62
	s_cselect_b32 s76, s26, s33
	s_cselect_b32 s77, s17, s56
	s_add_u32 s74, s78, 0x8000
	s_addc_u32 s75, s79, 0
	s_sub_u32 s74, s72, 0x4000
	s_subb_u32 s75, s73, 0
	v_lshl_add_u64 v[158:159], s[74:75], 0, v[130:131]
	s_mov_b32 m0, s51
	s_nop 0
	global_load_lds_dwordx4 v[158:159], off
	v_lshl_add_u64 v[158:159], s[74:75], 0, v[134:135]
	s_mov_b32 m0, s57
	s_nop 0
	global_load_lds_dwordx4 v[158:159], off
	v_lshl_add_u64 v[158:159], s[72:73], 0, v[138:139]
	s_add_i32 m0, s15, 0xc000
	ds_read_b128 v[198:201], v164
	ds_read_b128 v[202:205], v164 offset:1024
	ds_read_b128 v[206:209], v164 offset:2048
	ds_read_b128 v[210:213], v164 offset:3072
	ds_read_b128 v[214:217], v164 offset:4096
	ds_read_b128 v[218:221], v164 offset:5120
	ds_read_b128 v[222:225], v164 offset:6144
	ds_read_b128 v[226:229], v164 offset:7168
	global_load_lds_dwordx4 v[158:159], off
	v_lshl_add_u64 v[158:159], s[72:73], 0, v[140:141]
	s_add_i32 m0, s15, 0xe000
	s_nop 0
	global_load_lds_dwordx4 v[158:159], off
	s_waitcnt vmcnt(8)
	s_waitcnt lgkmcnt(0)
	s_barrier
	s_setprio 1
	s_waitcnt lgkmcnt(0)
	v_mfma_f32_16x16x32_bf16 v[126:129], v[146:149], v[198:201], v[126:129]
	v_mfma_f32_16x16x32_bf16 v[126:129], v[150:153], v[202:205], v[126:129]
	v_mfma_f32_16x16x32_bf16 v[110:113], v[146:149], v[206:209], v[110:113]
	v_mfma_f32_16x16x32_bf16 v[110:113], v[150:153], v[210:213], v[110:113]
	v_mfma_f32_16x16x32_bf16 v[94:97], v[146:149], v[214:217], v[94:97]
	v_mfma_f32_16x16x32_bf16 v[94:97], v[150:153], v[218:221], v[94:97]
	v_mfma_f32_16x16x32_bf16 v[78:81], v[146:149], v[222:225], v[78:81]
	v_mfma_f32_16x16x32_bf16 v[78:81], v[150:153], v[226:229], v[78:81]
	v_mfma_f32_16x16x32_bf16 v[122:125], v[154:157], v[198:201], v[122:125]
	v_mfma_f32_16x16x32_bf16 v[122:125], v[168:171], v[202:205], v[122:125]
	v_mfma_f32_16x16x32_bf16 v[106:109], v[154:157], v[206:209], v[106:109]
	v_mfma_f32_16x16x32_bf16 v[106:109], v[168:171], v[210:213], v[106:109]
	v_mfma_f32_16x16x32_bf16 v[90:93], v[154:157], v[214:217], v[90:93]
	v_mfma_f32_16x16x32_bf16 v[90:93], v[168:171], v[218:221], v[90:93]
	v_mfma_f32_16x16x32_bf16 v[74:77], v[154:157], v[222:225], v[74:77]
	v_mfma_f32_16x16x32_bf16 v[74:77], v[168:171], v[226:229], v[74:77]
	s_setprio 0
	s_setprio 1
	v_mfma_f32_16x16x32_bf16 v[118:121], v[172:175], v[198:201], v[118:121]
	v_mfma_f32_16x16x32_bf16 v[118:121], v[180:183], v[202:205], v[118:121]
	v_mfma_f32_16x16x32_bf16 v[102:105], v[172:175], v[206:209], v[102:105]
	v_mfma_f32_16x16x32_bf16 v[102:105], v[180:183], v[210:213], v[102:105]
	v_mfma_f32_16x16x32_bf16 v[86:89], v[172:175], v[214:217], v[86:89]
	v_mfma_f32_16x16x32_bf16 v[86:89], v[180:183], v[218:221], v[86:89]
	v_mfma_f32_16x16x32_bf16 v[70:73], v[172:175], v[222:225], v[70:73]
	v_mfma_f32_16x16x32_bf16 v[70:73], v[180:183], v[226:229], v[70:73]
	v_mfma_f32_16x16x32_bf16 v[114:117], v[184:187], v[198:201], v[114:117]
	v_mfma_f32_16x16x32_bf16 v[114:117], v[188:191], v[202:205], v[114:117]
	v_mfma_f32_16x16x32_bf16 v[98:101], v[184:187], v[206:209], v[98:101]
	v_mfma_f32_16x16x32_bf16 v[98:101], v[188:191], v[210:213], v[98:101]
	v_mfma_f32_16x16x32_bf16 v[82:85], v[184:187], v[214:217], v[82:85]
	v_mfma_f32_16x16x32_bf16 v[82:85], v[188:191], v[218:221], v[82:85]
	v_mfma_f32_16x16x32_bf16 v[66:69], v[184:187], v[222:225], v[66:69]
	v_mfma_f32_16x16x32_bf16 v[66:69], v[188:191], v[226:229], v[66:69]
	s_setprio 0
	s_barrier
	s_add_i32 s59, s81, s3
	v_lshl_add_u64 v[158:159], s[76:77], 0, v[132:133]
	s_mov_b32 m0, s59
	ds_read_b128 v[198:201], v164 offset:16384
	ds_read_b128 v[202:205], v164 offset:17408
	ds_read_b128 v[206:209], v164 offset:18432
	ds_read_b128 v[210:213], v164 offset:19456
	ds_read_b128 v[214:217], v164 offset:20480
	ds_read_b128 v[218:221], v164 offset:21504
	ds_read_b128 v[222:225], v164 offset:22528
	ds_read_b128 v[226:229], v164 offset:23552
	global_load_lds_dwordx4 v[158:159], off
	s_add_i32 m0, s59, 0x2000
	s_add_u32 s62, s76, 0x4000
	v_lshl_add_u64 v[158:159], s[76:77], 0, v[136:137]
	s_addc_u32 s63, s77, 0
	s_add_i32 s59, s82, s3
	global_load_lds_dwordx4 v[158:159], off
	v_lshl_add_u64 v[158:159], s[62:63], 0, v[132:133]
	s_mov_b32 m0, s59
	s_nop 0
	global_load_lds_dwordx4 v[158:159], off
	v_lshl_add_u64 v[158:159], s[62:63], 0, v[136:137]
	s_add_i32 m0, s59, 0x2000
	s_nop 0
	global_load_lds_dwordx4 v[158:159], off
	s_waitcnt vmcnt(6)
	s_waitcnt lgkmcnt(0)
	s_barrier
; #define PG8_STAGE(bufoff, gbase, voff) do { _Pragma("unroll") for (int _i = 0; _i < 2; ++_i) \
;         __builtin_amdgcn_global_load_lds((const unsigned*)((const char*)(gbase) + (voff)[_i]), (PG8_LAS unsigned*)(lds + (bufoff) + ldsw + _i * 8192), 16, 0, 0); } while (0)
; #define PG8_LDA(dst, b, h) do { _Pragma("unroll") for (int m = 0; m < 4; ++m) _Pragma("unroll") for (int k = 0; k < 2; ++k) dst[m][k] = *(const PG8_LAS bf16x8*)(lds + PG8_SA(b, h) + aoff + m * 2048 + k * 1024); } while (0)
; #define PG8_LDB(dst, b, h) do { _Pragma("unroll") for (int n = 0; n < 2; ++n) _Pragma("unroll") for (int k = 0; k < 2; ++k) dst[n][k] = *(const PG8_LAS bf16x8*)(lds + PG8_SB(b, h) + boff + n * 2048 + k * 1024); } while (0)
; #define PG8_MMA(ai, bj, At, Bt) do { __builtin_amdgcn_s_setprio(1); _Pragma("unroll") for (int m = 0; m < 4; ++m) _Pragma("unroll") for (int n = 0; n < 2; ++n) _Pragma("unroll") for (int k = 0; k < 2; ++k) \
;         acc[ai][bj][m][n] = __builtin_amdgcn_mfma_f32_16x16x32_bf16(Bt[n][k], At[m][k], acc[ai][bj][m][n], 0, 0, 0); __builtin_amdgcn_s_setprio(0); } while (0)
; #define PG8_BAR __builtin_amdgcn_s_barrier()
; template <class Epi, class Sched, bool ALIGN_EPI = false, bool SP2 = false>
; __device__ __forceinline__ void gemm_phase(PG8_LAS unsigned char* lds, const Gemm g, const Sched& S, const Epi& E) {
;     ...
;             if constexpr (SP2) {
;             PG8_LDB(B0, 0, 0); PG8_LDB(B1, 0, 1); PG8_SCHED; PG8_LDA(At, 0, 0); PG8_STAGE(PG8_SA(1, 1), a1 + hstep, voffA);
;             PG8_WAIT_V(8); PG8_WAIT_L(0); PG8_BAR; PG8_MMA(0, 0, At, B0); PG8_MMA(0, 1, At, B1); PG8_BAR; PG8_SCHED;
;             PG8_LDA(At, 0, 1); PG8_STAGE(PG8_SB(0, 0), b2, voffB); PG8_STAGE(PG8_SB(0, 1), b2 + hstep, voffB); PG8_STAGE(PG8_SA(0, 0), a2, voffA);
;             PG8_WAIT_V(8); PG8_WAIT_L(0); PG8_BAR; PG8_MMA(1, 0, At, B0); PG8_MMA(1, 1, At, B1); PG8_BAR; PG8_SCHED;
;             PG8_LDB(B0, 1, 0); PG8_LDB(B1, 1, 1); PG8_SCHED; PG8_LDA(At, 1, 0); PG8_STAGE(PG8_SA(0, 1), a2 + hstep, voffA);
;             PG8_WAIT_V(8); PG8_WAIT_L(0); PG8_BAR; PG8_MMA(0, 0, At, B0); PG8_MMA(0, 1, At, B1); PG8_BAR; PG8_SCHED;
;             PG8_LDA(At, 1, 1); PG8_STAGE(PG8_SB(1, 0), b3, voffB); PG8_STAGE(PG8_SB(1, 1), b3 + hstep, voffB); PG8_STAGE(PG8_SA(1, 0), a3, voffA);
;             PG8_WAIT_V(8); PG8_WAIT_L(0); PG8_BAR; PG8_MMA(1, 0, At, B0); PG8_MMA(1, 1, At, B1); PG8_BAR; PG8_SCHED;
	s_setprio 1
	s_waitcnt lgkmcnt(0)
	v_mfma_f32_16x16x32_bf16 v[62:65], v[146:149], v[198:201], v[62:65]
	v_mfma_f32_16x16x32_bf16 v[62:65], v[150:153], v[202:205], v[62:65]
	v_mfma_f32_16x16x32_bf16 v[46:49], v[146:149], v[206:209], v[46:49]
	v_mfma_f32_16x16x32_bf16 v[46:49], v[150:153], v[210:213], v[46:49]
	v_mfma_f32_16x16x32_bf16 v[30:33], v[146:149], v[214:217], v[30:33]
	v_mfma_f32_16x16x32_bf16 v[30:33], v[150:153], v[218:221], v[30:33]
	v_mfma_f32_16x16x32_bf16 v[14:17], v[146:149], v[222:225], v[14:17]
	v_mfma_f32_16x16x32_bf16 v[14:17], v[150:153], v[226:229], v[14:17]
	v_mfma_f32_16x16x32_bf16 v[58:61], v[154:157], v[198:201], v[58:61]
	v_mfma_f32_16x16x32_bf16 v[58:61], v[168:171], v[202:205], v[58:61]
	v_mfma_f32_16x16x32_bf16 v[42:45], v[154:157], v[206:209], v[42:45]
	v_mfma_f32_16x16x32_bf16 v[42:45], v[168:171], v[210:213], v[42:45]
	v_mfma_f32_16x16x32_bf16 v[26:29], v[154:157], v[214:217], v[26:29]
	v_mfma_f32_16x16x32_bf16 v[26:29], v[168:171], v[218:221], v[26:29]
	v_mfma_f32_16x16x32_bf16 v[10:13], v[154:157], v[222:225], v[10:13]
	v_mfma_f32_16x16x32_bf16 v[10:13], v[168:171], v[226:229], v[10:13]
	s_setprio 0
	s_setprio 1
	v_mfma_f32_16x16x32_bf16 v[54:57], v[172:175], v[198:201], v[54:57]
	v_mfma_f32_16x16x32_bf16 v[54:57], v[180:183], v[202:205], v[54:57]
	v_mfma_f32_16x16x32_bf16 v[38:41], v[172:175], v[206:209], v[38:41]
	v_mfma_f32_16x16x32_bf16 v[38:41], v[180:183], v[210:213], v[38:41]
	v_mfma_f32_16x16x32_bf16 v[22:25], v[172:175], v[214:217], v[22:25]
	v_mfma_f32_16x16x32_bf16 v[22:25], v[180:183], v[218:221], v[22:25]
	v_mfma_f32_16x16x32_bf16 v[6:9], v[172:175], v[222:225], v[6:9]
	v_mfma_f32_16x16x32_bf16 v[6:9], v[180:183], v[226:229], v[6:9]
	v_mfma_f32_16x16x32_bf16 v[50:53], v[184:187], v[198:201], v[50:53]
	v_mfma_f32_16x16x32_bf16 v[50:53], v[188:191], v[202:205], v[50:53]
	v_mfma_f32_16x16x32_bf16 v[34:37], v[184:187], v[206:209], v[34:37]
	v_mfma_f32_16x16x32_bf16 v[34:37], v[188:191], v[210:213], v[34:37]
	v_mfma_f32_16x16x32_bf16 v[18:21], v[184:187], v[214:217], v[18:21]
	v_mfma_f32_16x16x32_bf16 v[18:21], v[188:191], v[218:221], v[18:21]
	v_mfma_f32_16x16x32_bf16 v[2:5], v[184:187], v[222:225], v[2:5]
	v_mfma_f32_16x16x32_bf16 v[2:5], v[188:191], v[226:229], v[2:5]
	s_setprio 0
	s_barrier
	s_add_i32 s59, 0, 0x18000
	v_add_u32_e32 v158, s59, v160
	s_add_i32 s64, 0, 0x1c000
	ds_read_b128 v[146:149], v158
	ds_read_b128 v[150:153], v158 offset:1024
	ds_read_b128 v[154:157], v158 offset:2048
	ds_read_b128 v[168:171], v158 offset:3072
	v_add_u32_e32 v158, s64, v160
	ds_read_b128 v[172:175], v158
	ds_read_b128 v[180:183], v158 offset:1024
	ds_read_b128 v[184:187], v158 offset:2048
	ds_read_b128 v[188:191], v158 offset:3072
	v_lshl_add_u64 v[158:159], s[78:79], 0, v[130:131]
	s_mov_b32 m0, s15
	s_nop 0
	global_load_lds_dwordx4 v[158:159], off
	v_lshl_add_u64 v[158:159], s[78:79], 0, v[134:135]
	s_mov_b32 m0, s27
	s_nop 0
	global_load_lds_dwordx4 v[158:159], off
	s_add_u32 s62, s78, 0x4000
	s_addc_u32 s63, s79, 0
	s_mov_b32 m0, s28
	v_lshl_add_u64 v[158:159], s[62:63], 0, v[130:131]
	ds_read_b128 v[198:201], v164 offset:32768
	ds_read_b128 v[202:205], v164 offset:33792
	ds_read_b128 v[206:209], v164 offset:34816
	ds_read_b128 v[210:213], v164 offset:35840
	ds_read_b128 v[214:217], v164 offset:36864
	ds_read_b128 v[218:221], v164 offset:37888
	ds_read_b128 v[222:225], v164 offset:38912
	ds_read_b128 v[226:229], v164 offset:39936
	global_load_lds_dwordx4 v[158:159], off
	v_lshl_add_u64 v[158:159], s[62:63], 0, v[134:135]
	s_mov_b32 m0, s29
	s_nop 0
	global_load_lds_dwordx4 v[158:159], off
	s_waitcnt vmcnt(8)
	s_waitcnt lgkmcnt(0)
	s_barrier
; #define PG8_STAGE(bufoff, gbase, voff) do { _Pragma("unroll") for (int _i = 0; _i < 2; ++_i) \
;         __builtin_amdgcn_global_load_lds((const unsigned*)((const char*)(gbase) + (voff)[_i]), (PG8_LAS unsigned*)(lds + (bufoff) + ldsw + _i * 8192), 16, 0, 0); } while (0)
; #define PG8_LDA(dst, b, h) do { _Pragma("unroll") for (int m = 0; m < 4; ++m) _Pragma("unroll") for (int k = 0; k < 2; ++k) dst[m][k] = *(const PG8_LAS bf16x8*)(lds + PG8_SA(b, h) + aoff + m * 2048 + k * 1024); } while (0)
; #define PG8_LDB(dst, b, h) do { _Pragma("unroll") for (int n = 0; n < 2; ++n) _Pragma("unroll") for (int k = 0; k < 2; ++k) dst[n][k] = *(const PG8_LAS bf16x8*)(lds + PG8_SB(b, h) + boff + n * 2048 + k * 1024); } while (0)
; #define PG8_MMA(ai, bj, At, Bt) do { __builtin_amdgcn_s_setprio(1); _Pragma("unroll") for (int m = 0; m < 4; ++m) _Pragma("unroll") for (int n = 0; n < 2; ++n) _Pragma("unroll") for (int k = 0; k < 2; ++k) \
;         acc[ai][bj][m][n] = __builtin_amdgcn_mfma_f32_16x16x32_bf16(Bt[n][k], At[m][k], acc[ai][bj][m][n], 0, 0, 0); __builtin_amdgcn_s_setprio(0); } while (0)
; #define PG8_BAR __builtin_amdgcn_s_barrier()
; template <class Epi, class Sched, bool ALIGN_EPI = false, bool SP2 = false>
; __device__ __forceinline__ void gemm_phase(PG8_LAS unsigned char* lds, const Gemm g, const Sched& S, const Epi& E) {
;     ...
;             if constexpr (SP2) {
;             PG8_LDB(B0, 0, 0); PG8_LDB(B1, 0, 1); PG8_SCHED; PG8_LDA(At, 0, 0); PG8_STAGE(PG8_SA(1, 1), a1 + hstep, voffA);
;             PG8_WAIT_V(8); PG8_WAIT_L(0); PG8_BAR; PG8_MMA(0, 0, At, B0); PG8_MMA(0, 1, At, B1); PG8_BAR; PG8_SCHED;
;             PG8_LDA(At, 0, 1); PG8_STAGE(PG8_SB(0, 0), b2, voffB); PG8_STAGE(PG8_SB(0, 1), b2 + hstep, voffB); PG8_STAGE(PG8_SA(0, 0), a2, voffA);
;             PG8_WAIT_V(8); PG8_WAIT_L(0); PG8_BAR; PG8_MMA(1, 0, At, B0); PG8_MMA(1, 1, At, B1); PG8_BAR; PG8_SCHED;
;             PG8_LDB(B0, 1, 0); PG8_LDB(B1, 1, 1); PG8_SCHED; PG8_LDA(At, 1, 0); PG8_STAGE(PG8_SA(0, 1), a2 + hstep, voffA);
;             PG8_WAIT_V(8); PG8_WAIT_L(0); PG8_BAR; PG8_MMA(0, 0, At, B0); PG8_MMA(0, 1, At, B1); PG8_BAR; PG8_SCHED;
;             PG8_LDA(At, 1, 1); PG8_STAGE(PG8_SB(1, 0), b3, voffB); PG8_STAGE(PG8_SB(1, 1), b3 + hstep, voffB); PG8_STAGE(PG8_SA(1, 0), a3, voffA);
;             PG8_WAIT_V(8); PG8_WAIT_L(0); PG8_BAR; PG8_MMA(1, 0, At, B0); PG8_MMA(1, 1, At, B1); PG8_BAR; PG8_SCHED;
	s_setprio 1
	s_waitcnt lgkmcnt(0)
	v_mfma_f32_16x16x32_bf16 v[126:129], v[146:149], v[198:201], v[126:129]
	v_mfma_f32_16x16x32_bf16 v[126:129], v[150:153], v[202:205], v[126:129]
	v_mfma_f32_16x16x32_bf16 v[110:113], v[146:149], v[206:209], v[110:113]
	v_mfma_f32_16x16x32_bf16 v[110:113], v[150:153], v[210:213], v[110:113]
	v_mfma_f32_16x16x32_bf16 v[94:97], v[146:149], v[214:217], v[94:97]
	v_mfma_f32_16x16x32_bf16 v[94:97], v[150:153], v[218:221], v[94:97]
	v_mfma_f32_16x16x32_bf16 v[78:81], v[146:149], v[222:225], v[78:81]
	v_mfma_f32_16x16x32_bf16 v[78:81], v[150:153], v[226:229], v[78:81]
	v_mfma_f32_16x16x32_bf16 v[122:125], v[154:157], v[198:201], v[122:125]
	v_mfma_f32_16x16x32_bf16 v[122:125], v[168:171], v[202:205], v[122:125]
	v_mfma_f32_16x16x32_bf16 v[106:109], v[154:157], v[206:209], v[106:109]
	v_mfma_f32_16x16x32_bf16 v[106:109], v[168:171], v[210:213], v[106:109]
	v_mfma_f32_16x16x32_bf16 v[90:93], v[154:157], v[214:217], v[90:93]
	v_mfma_f32_16x16x32_bf16 v[90:93], v[168:171], v[218:221], v[90:93]
	v_mfma_f32_16x16x32_bf16 v[74:77], v[154:157], v[222:225], v[74:77]
	v_mfma_f32_16x16x32_bf16 v[74:77], v[168:171], v[226:229], v[74:77]
	s_setprio 0
	s_setprio 1
	v_mfma_f32_16x16x32_bf16 v[118:121], v[172:175], v[198:201], v[118:121]
	v_mfma_f32_16x16x32_bf16 v[118:121], v[180:183], v[202:205], v[118:121]
	v_mfma_f32_16x16x32_bf16 v[102:105], v[172:175], v[206:209], v[102:105]
	v_mfma_f32_16x16x32_bf16 v[102:105], v[180:183], v[210:213], v[102:105]
	v_mfma_f32_16x16x32_bf16 v[86:89], v[172:175], v[214:217], v[86:89]
	v_mfma_f32_16x16x32_bf16 v[86:89], v[180:183], v[218:221], v[86:89]
	v_mfma_f32_16x16x32_bf16 v[70:73], v[172:175], v[222:225], v[70:73]
	v_mfma_f32_16x16x32_bf16 v[70:73], v[180:183], v[226:229], v[70:73]
	v_mfma_f32_16x16x32_bf16 v[114:117], v[184:187], v[198:201], v[114:117]
	v_mfma_f32_16x16x32_bf16 v[114:117], v[188:191], v[202:205], v[114:117]
	v_mfma_f32_16x16x32_bf16 v[98:101], v[184:187], v[206:209], v[98:101]
	v_mfma_f32_16x16x32_bf16 v[98:101], v[188:191], v[210:213], v[98:101]
	v_mfma_f32_16x16x32_bf16 v[82:85], v[184:187], v[214:217], v[82:85]
	v_mfma_f32_16x16x32_bf16 v[82:85], v[188:191], v[218:221], v[82:85]
	v_mfma_f32_16x16x32_bf16 v[66:69], v[184:187], v[222:225], v[66:69]
	v_mfma_f32_16x16x32_bf16 v[66:69], v[188:191], v[226:229], v[66:69]
	s_setprio 0
	s_barrier
	s_add_u32 s62, s76, 0x8000
	s_addc_u32 s63, s77, 0
	s_add_i32 s59, s59, s3
	v_lshl_add_u64 v[158:159], s[62:63], 0, v[132:133]
	s_mov_b32 m0, s59
	ds_read_b128 v[198:201], v164 offset:49152
	ds_read_b128 v[202:205], v164 offset:50176
	ds_read_b128 v[206:209], v164 offset:51200
	ds_read_b128 v[210:213], v164 offset:52224
	ds_read_b128 v[214:217], v164 offset:53248
	ds_read_b128 v[218:221], v164 offset:54272
	ds_read_b128 v[222:225], v164 offset:55296
	ds_read_b128 v[226:229], v164 offset:56320
	global_load_lds_dwordx4 v[158:159], off
	s_add_i32 m0, s59, 0x2000
	v_lshl_add_u64 v[158:159], s[62:63], 0, v[136:137]
	s_add_u32 s62, s76, 0xc000
	s_addc_u32 s63, s77, 0
	s_add_i32 s59, s64, s3
	global_load_lds_dwordx4 v[158:159], off
	v_lshl_add_u64 v[158:159], s[62:63], 0, v[132:133]
	s_mov_b32 m0, s59
	s_nop 0
	global_load_lds_dwordx4 v[158:159], off
	v_lshl_add_u64 v[158:159], s[62:63], 0, v[136:137]
	s_add_i32 m0, s59, 0x2000
	s_nop 0
	global_load_lds_dwordx4 v[158:159], off
	s_waitcnt vmcnt(6)
	s_waitcnt lgkmcnt(0)
	s_barrier
	s_setprio 1
	s_waitcnt lgkmcnt(0)
	v_mfma_f32_16x16x32_bf16 v[62:65], v[146:149], v[198:201], v[62:65]
	v_mfma_f32_16x16x32_bf16 v[62:65], v[150:153], v[202:205], v[62:65]
	v_mfma_f32_16x16x32_bf16 v[46:49], v[146:149], v[206:209], v[46:49]
	v_mfma_f32_16x16x32_bf16 v[46:49], v[150:153], v[210:213], v[46:49]
	v_mfma_f32_16x16x32_bf16 v[30:33], v[146:149], v[214:217], v[30:33]
	v_mfma_f32_16x16x32_bf16 v[30:33], v[150:153], v[218:221], v[30:33]
	v_mfma_f32_16x16x32_bf16 v[14:17], v[146:149], v[222:225], v[14:17]
	v_mfma_f32_16x16x32_bf16 v[14:17], v[150:153], v[226:229], v[14:17]
	v_mfma_f32_16x16x32_bf16 v[58:61], v[154:157], v[198:201], v[58:61]
	v_mfma_f32_16x16x32_bf16 v[58:61], v[168:171], v[202:205], v[58:61]
	v_mfma_f32_16x16x32_bf16 v[42:45], v[154:157], v[206:209], v[42:45]
	v_mfma_f32_16x16x32_bf16 v[42:45], v[168:171], v[210:213], v[42:45]
	v_mfma_f32_16x16x32_bf16 v[26:29], v[154:157], v[214:217], v[26:29]
	v_mfma_f32_16x16x32_bf16 v[26:29], v[168:171], v[218:221], v[26:29]
	v_mfma_f32_16x16x32_bf16 v[10:13], v[154:157], v[222:225], v[10:13]
	v_mfma_f32_16x16x32_bf16 v[10:13], v[168:171], v[226:229], v[10:13]
	s_setprio 0
	s_setprio 1
	v_mfma_f32_16x16x32_bf16 v[54:57], v[172:175], v[198:201], v[54:57]
	v_mfma_f32_16x16x32_bf16 v[54:57], v[180:183], v[202:205], v[54:57]
	v_mfma_f32_16x16x32_bf16 v[38:41], v[172:175], v[206:209], v[38:41]
	v_mfma_f32_16x16x32_bf16 v[38:41], v[180:183], v[210:213], v[38:41]
	v_mfma_f32_16x16x32_bf16 v[22:25], v[172:175], v[214:217], v[22:25]
	v_mfma_f32_16x16x32_bf16 v[22:25], v[180:183], v[218:221], v[22:25]
	v_mfma_f32_16x16x32_bf16 v[6:9], v[172:175], v[222:225], v[6:9]
	v_mfma_f32_16x16x32_bf16 v[6:9], v[180:183], v[226:229], v[6:9]
	v_mfma_f32_16x16x32_bf16 v[50:53], v[184:187], v[198:201], v[50:53]
	v_mfma_f32_16x16x32_bf16 v[50:53], v[188:191], v[202:205], v[50:53]
	v_mfma_f32_16x16x32_bf16 v[34:37], v[184:187], v[206:209], v[34:37]
	v_mfma_f32_16x16x32_bf16 v[34:37], v[188:191], v[210:213], v[34:37]
	v_mfma_f32_16x16x32_bf16 v[18:21], v[184:187], v[214:217], v[18:21]
	v_mfma_f32_16x16x32_bf16 v[18:21], v[188:191], v[218:221], v[18:21]
	v_mfma_f32_16x16x32_bf16 v[2:5], v[184:187], v[222:225], v[2:5]
	v_mfma_f32_16x16x32_bf16 v[2:5], v[188:191], v[226:229], v[2:5]
	s_setprio 0
	s_barrier
	s_add_i32 s58, s58, 2
	s_add_u32 s72, s72, 0x10000
	s_addc_u32 s73, s73, 0
	s_add_u32 s33, s33, 0x10000
	s_addc_u32 s56, s56, 0
	s_cmp_gt_u32 s58, 61
	s_cbranch_scc0 .LBB0_290
	s_and_b64 vcc, exec, s[12:13]
	s_cbranch_vccz .LBB0_293
	s_barrier

; #define PG8_STAGE(bufoff, gbase, voff) do { _Pragma("unroll") for (int _i = 0; _i < 2; ++_i) \
;         __builtin_amdgcn_global_load_lds((const unsigned*)((const char*)(gbase) + (voff)[_i]), (PG8_LAS unsigned*)(lds + (bufoff) + ldsw + _i * 8192), 16, 0, 0); } while (0)
; #define PG8_LDA(dst, b, h) do { _Pragma("unroll") for (int m = 0; m < 4; ++m) _Pragma("unroll") for (int k = 0; k < 2; ++k) dst[m][k] = *(const PG8_LAS bf16x8*)(lds + PG8_SA(b, h) + aoff + m * 2048 + k * 1024); } while (0)
; #define PG8_LDB(dst, b, h) do { _Pragma("unroll") for (int n = 0; n < 2; ++n) _Pragma("unroll") for (int k = 0; k < 2; ++k) dst[n][k] = *(const PG8_LAS bf16x8*)(lds + PG8_SB(b, h) + boff + n * 2048 + k * 1024); } while (0)
; #define PG8_WAIT_V(n) asm volatile("s_waitcnt vmcnt(" #n ")" ::: "memory")
; template <class Epi, class Sched, bool ALIGN_EPI = false, bool SP2 = false>
; __device__ __forceinline__ void gemm_phase(PG8_LAS unsigned char* lds, const Gemm g, const Sched& S, const Epi& E) {
;     ...
;             const char* a1 = cA + (size_t)(t + 1) * kstep;
;             const char* a2 = last ? nA : cA + (size_t)(t + 2) * kstep; const char* b2 = last ? nB : cB + (size_t)(t + 2) * kstep;
;             const char* a3 = a2 + kstep; const char* b3 = b2 + kstep;
;             if (last && has_next) S.a_ready(nxt);
;             if constexpr (SP2) {
;             PG8_LDB(B0, 0, 0); PG8_LDB(B1, 0, 1); PG8_SCHED; PG8_LDA(At, 0, 0); PG8_STAGE(PG8_SA(1, 1), a1 + hstep, voffA);
;             PG8_WAIT_V(8); PG8_WAIT_L(0); PG8_BAR; PG8_MMA(0, 0, At, B0); PG8_MMA(0, 1, At, B1); PG8_BAR; PG8_SCHED;
;             PG8_LDA(At, 0, 1); PG8_STAGE(PG8_SB(0, 0), b2, voffB); PG8_STAGE(PG8_SB(0, 1), b2 + hstep, voffB); PG8_STAGE(PG8_SA(0, 0), a2, voffA);
;             PG8_WAIT_V(8); PG8_WAIT_L(0); PG8_BAR; PG8_MMA(1, 0, At, B0); PG8_MMA(1, 1, At, B1); PG8_BAR; PG8_SCHED;
;             PG8_LDB(B0, 1, 0); PG8_LDB(B1, 1, 1); PG8_SCHED; PG8_LDA(At, 1, 0); PG8_STAGE(PG8_SA(0, 1), a2 + hstep, voffA);
;             PG8_WAIT_V(8); PG8_WAIT_L(0); PG8_BAR; PG8_MMA(0, 0, At, B0); PG8_MMA(0, 1, At, B1); PG8_BAR; PG8_SCHED;
;             PG8_LDA(At, 1, 1); PG8_STAGE(PG8_SB(1, 0), b3, voffB); PG8_STAGE(PG8_SB(1, 1), b3 + hstep, voffB); PG8_STAGE(PG8_SA(1, 0), a3, voffA);
;             PG8_WAIT_V(8); PG8_WAIT_L(0); PG8_BAR; PG8_MMA(1, 0, At, B0); PG8_MMA(1, 1, At, B1); PG8_BAR; PG8_SCHED;
.LBB0_757:
	ds_read_b128 v[154:157], v149
	ds_read_b128 v[158:161], v149 offset:1024
	ds_read_b128 v[162:165], v149 offset:2048
	ds_read_b128 v[166:169], v149 offset:3072
	ds_read_b128 v[170:173], v150
	ds_read_b128 v[174:177], v150 offset:1024
	ds_read_b128 v[180:183], v150 offset:2048
	ds_read_b128 v[184:187], v150 offset:3072
	s_add_u32 s46, s44, 0x4000
	s_addc_u32 s47, s45, 0
	s_cmp_eq_u32 s70, 60
	s_cselect_b32 s50, s39, s46
	s_cselect_b32 s51, s17, s47
	s_cselect_b32 s48, s41, s68
	s_cselect_b32 s49, s15, s69
	s_add_u32 s46, s50, 0x8000
	s_addc_u32 s47, s51, 0
	s_sub_u32 s46, s44, 0x4000
	s_subb_u32 s47, s45, 0
	v_lshl_add_u64 v[146:147], s[46:47], 0, v[130:131]
	s_mov_b32 m0, s57
	s_nop 0
	global_load_lds_dwordx4 v[146:147], off
	v_lshl_add_u64 v[146:147], s[46:47], 0, v[134:135]
	s_mov_b32 m0, s58
	s_nop 0
	global_load_lds_dwordx4 v[146:147], off
	v_lshl_add_u64 v[146:147], s[44:45], 0, v[138:139]
	s_add_i32 m0, s26, 0xc000
	ds_read_b128 v[188:191], v151
	ds_read_b128 v[198:201], v151 offset:1024
	ds_read_b128 v[202:205], v151 offset:2048
	ds_read_b128 v[206:209], v151 offset:3072
	ds_read_b128 v[210:213], v151 offset:4096
	ds_read_b128 v[214:217], v151 offset:5120
	ds_read_b128 v[218:221], v151 offset:6144
	ds_read_b128 v[222:225], v151 offset:7168
	global_load_lds_dwordx4 v[146:147], off
	v_lshl_add_u64 v[146:147], s[44:45], 0, v[140:141]
	s_add_i32 m0, s26, 0xe000
	s_nop 0
	global_load_lds_dwordx4 v[146:147], off
	s_waitcnt vmcnt(8)
	s_waitcnt lgkmcnt(0)
	s_barrier
	s_setprio 1
	s_waitcnt lgkmcnt(0)
	v_mfma_f32_16x16x32_bf16 v[126:129], v[154:157], v[188:191], v[126:129]
	v_mfma_f32_16x16x32_bf16 v[126:129], v[158:161], v[198:201], v[126:129]
	v_mfma_f32_16x16x32_bf16 v[110:113], v[154:157], v[202:205], v[110:113]
	v_mfma_f32_16x16x32_bf16 v[110:113], v[158:161], v[206:209], v[110:113]
	v_mfma_f32_16x16x32_bf16 v[94:97], v[154:157], v[210:213], v[94:97]
	v_mfma_f32_16x16x32_bf16 v[94:97], v[158:161], v[214:217], v[94:97]
	v_mfma_f32_16x16x32_bf16 v[78:81], v[154:157], v[218:221], v[78:81]
	v_mfma_f32_16x16x32_bf16 v[78:81], v[158:161], v[222:225], v[78:81]
	v_mfma_f32_16x16x32_bf16 v[122:125], v[162:165], v[188:191], v[122:125]
	v_mfma_f32_16x16x32_bf16 v[122:125], v[166:169], v[198:201], v[122:125]
	v_mfma_f32_16x16x32_bf16 v[106:109], v[162:165], v[202:205], v[106:109]
	v_mfma_f32_16x16x32_bf16 v[106:109], v[166:169], v[206:209], v[106:109]
	v_mfma_f32_16x16x32_bf16 v[90:93], v[162:165], v[210:213], v[90:93]
	v_mfma_f32_16x16x32_bf16 v[90:93], v[166:169], v[214:217], v[90:93]
	v_mfma_f32_16x16x32_bf16 v[74:77], v[162:165], v[218:221], v[74:77]
	v_mfma_f32_16x16x32_bf16 v[74:77], v[166:169], v[222:225], v[74:77]
	s_setprio 0
	s_setprio 1
	v_mfma_f32_16x16x32_bf16 v[118:121], v[170:173], v[188:191], v[118:121]
	v_mfma_f32_16x16x32_bf16 v[118:121], v[174:177], v[198:201], v[118:121]
	v_mfma_f32_16x16x32_bf16 v[102:105], v[170:173], v[202:205], v[102:105]
	v_mfma_f32_16x16x32_bf16 v[102:105], v[174:177], v[206:209], v[102:105]
	v_mfma_f32_16x16x32_bf16 v[86:89], v[170:173], v[210:213], v[86:89]
	v_mfma_f32_16x16x32_bf16 v[86:89], v[174:177], v[214:217], v[86:89]
	v_mfma_f32_16x16x32_bf16 v[70:73], v[170:173], v[218:221], v[70:73]
	v_mfma_f32_16x16x32_bf16 v[70:73], v[174:177], v[222:225], v[70:73]
	v_mfma_f32_16x16x32_bf16 v[114:117], v[180:183], v[188:191], v[114:117]
	v_mfma_f32_16x16x32_bf16 v[114:117], v[184:187], v[198:201], v[114:117]
	v_mfma_f32_16x16x32_bf16 v[98:101], v[180:183], v[202:205], v[98:101]
	v_mfma_f32_16x16x32_bf16 v[98:101], v[184:187], v[206:209], v[98:101]
	v_mfma_f32_16x16x32_bf16 v[82:85], v[180:183], v[210:213], v[82:85]
	v_mfma_f32_16x16x32_bf16 v[82:85], v[184:187], v[214:217], v[82:85]
	v_mfma_f32_16x16x32_bf16 v[66:69], v[180:183], v[218:221], v[66:69]
	v_mfma_f32_16x16x32_bf16 v[66:69], v[184:187], v[222:225], v[66:69]
	s_setprio 0
	s_barrier
	s_add_i32 s71, s59, s3
	v_lshl_add_u64 v[146:147], s[48:49], 0, v[132:133]
	s_mov_b32 m0, s71
	ds_read_b128 v[188:191], v151 offset:16384
	ds_read_b128 v[198:201], v151 offset:17408
	ds_read_b128 v[202:205], v151 offset:18432
	ds_read_b128 v[206:209], v151 offset:19456
	ds_read_b128 v[210:213], v151 offset:20480
	ds_read_b128 v[214:217], v151 offset:21504
	ds_read_b128 v[218:221], v151 offset:22528
	ds_read_b128 v[222:225], v151 offset:23552
	global_load_lds_dwordx4 v[146:147], off
	s_add_i32 m0, s71, 0x2000
	s_add_u32 s72, s48, 0x4000
	v_lshl_add_u64 v[146:147], s[48:49], 0, v[136:137]
	s_addc_u32 s73, s49, 0
	s_add_i32 s71, s61, s3
	global_load_lds_dwordx4 v[146:147], off
	v_lshl_add_u64 v[146:147], s[72:73], 0, v[132:133]
	s_mov_b32 m0, s71
	s_nop 0
	global_load_lds_dwordx4 v[146:147], off
	v_lshl_add_u64 v[146:147], s[72:73], 0, v[136:137]
	s_add_i32 m0, s71, 0x2000
	s_nop 0
	global_load_lds_dwordx4 v[146:147], off
	s_waitcnt vmcnt(6)
	s_waitcnt lgkmcnt(0)
	s_barrier
; #define PG8_STAGE(bufoff, gbase, voff) do { _Pragma("unroll") for (int _i = 0; _i < 2; ++_i) \
;         __builtin_amdgcn_global_load_lds((const unsigned*)((const char*)(gbase) + (voff)[_i]), (PG8_LAS unsigned*)(lds + (bufoff) + ldsw + _i * 8192), 16, 0, 0); } while (0)
; #define PG8_LDA(dst, b, h) do { _Pragma("unroll") for (int m = 0; m < 4; ++m) _Pragma("unroll") for (int k = 0; k < 2; ++k) dst[m][k] = *(const PG8_LAS bf16x8*)(lds + PG8_SA(b, h) + aoff + m * 2048 + k * 1024); } while (0)
; #define PG8_LDB(dst, b, h) do { _Pragma("unroll") for (int n = 0; n < 2; ++n) _Pragma("unroll") for (int k = 0; k < 2; ++k) dst[n][k] = *(const PG8_LAS bf16x8*)(lds + PG8_SB(b, h) + boff + n * 2048 + k * 1024); } while (0)
; #define PG8_MMA(ai, bj, At, Bt) do { __builtin_amdgcn_s_setprio(1); _Pragma("unroll") for (int m = 0; m < 4; ++m) _Pragma("unroll") for (int n = 0; n < 2; ++n) _Pragma("unroll") for (int k = 0; k < 2; ++k) \
;         acc[ai][bj][m][n] = __builtin_amdgcn_mfma_f32_16x16x32_bf16(Bt[n][k], At[m][k], acc[ai][bj][m][n], 0, 0, 0); __builtin_amdgcn_s_setprio(0); } while (0)
; #define PG8_BAR __builtin_amdgcn_s_barrier()
; template <class Epi, class Sched, bool ALIGN_EPI = false, bool SP2 = false>
; __device__ __forceinline__ void gemm_phase(PG8_LAS unsigned char* lds, const Gemm g, const Sched& S, const Epi& E) {
;     ...
;             if constexpr (SP2) {
;             PG8_LDB(B0, 0, 0); PG8_LDB(B1, 0, 1); PG8_SCHED; PG8_LDA(At, 0, 0); PG8_STAGE(PG8_SA(1, 1), a1 + hstep, voffA);
;             PG8_WAIT_V(8); PG8_WAIT_L(0); PG8_BAR; PG8_MMA(0, 0, At, B0); PG8_MMA(0, 1, At, B1); PG8_BAR; PG8_SCHED;
;             PG8_LDA(At, 0, 1); PG8_STAGE(PG8_SB(0, 0), b2, voffB); PG8_STAGE(PG8_SB(0, 1), b2 + hstep, voffB); PG8_STAGE(PG8_SA(0, 0), a2, voffA);
;             PG8_WAIT_V(8); PG8_WAIT_L(0); PG8_BAR; PG8_MMA(1, 0, At, B0); PG8_MMA(1, 1, At, B1); PG8_BAR; PG8_SCHED;
;             PG8_LDB(B0, 1, 0); PG8_LDB(B1, 1, 1); PG8_SCHED; PG8_LDA(At, 1, 0); PG8_STAGE(PG8_SA(0, 1), a2 + hstep, voffA);
;             PG8_WAIT_V(8); PG8_WAIT_L(0); PG8_BAR; PG8_MMA(0, 0, At, B0); PG8_MMA(0, 1, At, B1); PG8_BAR; PG8_SCHED;
;             PG8_LDA(At, 1, 1); PG8_STAGE(PG8_SB(1, 0), b3, voffB); PG8_STAGE(PG8_SB(1, 1), b3 + hstep, voffB); PG8_STAGE(PG8_SA(1, 0), a3, voffA);
;             PG8_WAIT_V(8); PG8_WAIT_L(0); PG8_BAR; PG8_MMA(1, 0, At, B0); PG8_MMA(1, 1, At, B1); PG8_BAR; PG8_SCHED;
	s_setprio 1
	s_waitcnt lgkmcnt(0)
	v_mfma_f32_16x16x32_bf16 v[62:65], v[154:157], v[188:191], v[62:65]
	v_mfma_f32_16x16x32_bf16 v[62:65], v[158:161], v[198:201], v[62:65]
	v_mfma_f32_16x16x32_bf16 v[46:49], v[154:157], v[202:205], v[46:49]
	v_mfma_f32_16x16x32_bf16 v[46:49], v[158:161], v[206:209], v[46:49]
	v_mfma_f32_16x16x32_bf16 v[30:33], v[154:157], v[210:213], v[30:33]
	v_mfma_f32_16x16x32_bf16 v[30:33], v[158:161], v[214:217], v[30:33]
	v_mfma_f32_16x16x32_bf16 v[14:17], v[154:157], v[218:221], v[14:17]
	v_mfma_f32_16x16x32_bf16 v[14:17], v[158:161], v[222:225], v[14:17]
	v_mfma_f32_16x16x32_bf16 v[58:61], v[162:165], v[188:191], v[58:61]
	v_mfma_f32_16x16x32_bf16 v[58:61], v[166:169], v[198:201], v[58:61]
	v_mfma_f32_16x16x32_bf16 v[42:45], v[162:165], v[202:205], v[42:45]
	v_mfma_f32_16x16x32_bf16 v[42:45], v[166:169], v[206:209], v[42:45]
	v_mfma_f32_16x16x32_bf16 v[26:29], v[162:165], v[210:213], v[26:29]
	v_mfma_f32_16x16x32_bf16 v[26:29], v[166:169], v[214:217], v[26:29]
	v_mfma_f32_16x16x32_bf16 v[10:13], v[162:165], v[218:221], v[10:13]
	v_mfma_f32_16x16x32_bf16 v[10:13], v[166:169], v[222:225], v[10:13]
	s_setprio 0
	s_setprio 1
	v_mfma_f32_16x16x32_bf16 v[54:57], v[170:173], v[188:191], v[54:57]
	v_mfma_f32_16x16x32_bf16 v[54:57], v[174:177], v[198:201], v[54:57]
	v_mfma_f32_16x16x32_bf16 v[38:41], v[170:173], v[202:205], v[38:41]
	v_mfma_f32_16x16x32_bf16 v[38:41], v[174:177], v[206:209], v[38:41]
	v_mfma_f32_16x16x32_bf16 v[22:25], v[170:173], v[210:213], v[22:25]
	v_mfma_f32_16x16x32_bf16 v[22:25], v[174:177], v[214:217], v[22:25]
	v_mfma_f32_16x16x32_bf16 v[6:9], v[170:173], v[218:221], v[6:9]
	v_mfma_f32_16x16x32_bf16 v[6:9], v[174:177], v[222:225], v[6:9]
	v_mfma_f32_16x16x32_bf16 v[50:53], v[180:183], v[188:191], v[50:53]
	v_mfma_f32_16x16x32_bf16 v[50:53], v[184:187], v[198:201], v[50:53]
	v_mfma_f32_16x16x32_bf16 v[34:37], v[180:183], v[202:205], v[34:37]
	v_mfma_f32_16x16x32_bf16 v[34:37], v[184:187], v[206:209], v[34:37]
	v_mfma_f32_16x16x32_bf16 v[18:21], v[180:183], v[210:213], v[18:21]
	v_mfma_f32_16x16x32_bf16 v[18:21], v[184:187], v[214:217], v[18:21]
	v_mfma_f32_16x16x32_bf16 v[2:5], v[180:183], v[218:221], v[2:5]
	v_mfma_f32_16x16x32_bf16 v[2:5], v[184:187], v[222:225], v[2:5]
	s_setprio 0
	s_barrier
	s_add_i32 s71, 0, 0x18000
	v_add_u32_e32 v146, s71, v1
	s_add_i32 s72, 0, 0x1c000
	ds_read_b128 v[154:157], v146
	ds_read_b128 v[158:161], v146 offset:1024
	ds_read_b128 v[162:165], v146 offset:2048
	ds_read_b128 v[166:169], v146 offset:3072
	v_add_u32_e32 v146, s72, v1
	ds_read_b128 v[170:173], v146
	ds_read_b128 v[174:177], v146 offset:1024
	ds_read_b128 v[180:183], v146 offset:2048
	ds_read_b128 v[184:187], v146 offset:3072
	v_lshl_add_u64 v[146:147], s[50:51], 0, v[130:131]
	s_mov_b32 m0, s26
	s_nop 0
	global_load_lds_dwordx4 v[146:147], off
	v_lshl_add_u64 v[146:147], s[50:51], 0, v[134:135]
	s_mov_b32 m0, s27
	s_nop 0
	global_load_lds_dwordx4 v[146:147], off
	s_add_u32 s50, s50, 0x4000
	s_addc_u32 s51, s51, 0
	s_mov_b32 m0, s28
	v_lshl_add_u64 v[146:147], s[50:51], 0, v[130:131]
	ds_read_b128 v[188:191], v151 offset:32768
	ds_read_b128 v[198:201], v151 offset:33792
	ds_read_b128 v[202:205], v151 offset:34816
	ds_read_b128 v[206:209], v151 offset:35840
	ds_read_b128 v[210:213], v151 offset:36864
	ds_read_b128 v[214:217], v151 offset:37888
	ds_read_b128 v[218:221], v151 offset:38912
	ds_read_b128 v[222:225], v151 offset:39936
	global_load_lds_dwordx4 v[146:147], off
	v_lshl_add_u64 v[146:147], s[50:51], 0, v[134:135]
	s_mov_b32 m0, s29
	s_nop 0
	global_load_lds_dwordx4 v[146:147], off
	s_waitcnt vmcnt(8)
	s_waitcnt lgkmcnt(0)
	s_barrier
; #define PG8_STAGE(bufoff, gbase, voff) do { _Pragma("unroll") for (int _i = 0; _i < 2; ++_i) \
;         __builtin_amdgcn_global_load_lds((const unsigned*)((const char*)(gbase) + (voff)[_i]), (PG8_LAS unsigned*)(lds + (bufoff) + ldsw + _i * 8192), 16, 0, 0); } while (0)
; #define PG8_LDA(dst, b, h) do { _Pragma("unroll") for (int m = 0; m < 4; ++m) _Pragma("unroll") for (int k = 0; k < 2; ++k) dst[m][k] = *(const PG8_LAS bf16x8*)(lds + PG8_SA(b, h) + aoff + m * 2048 + k * 1024); } while (0)
; #define PG8_LDB(dst, b, h) do { _Pragma("unroll") for (int n = 0; n < 2; ++n) _Pragma("unroll") for (int k = 0; k < 2; ++k) dst[n][k] = *(const PG8_LAS bf16x8*)(lds + PG8_SB(b, h) + boff + n * 2048 + k * 1024); } while (0)
; #define PG8_MMA(ai, bj, At, Bt) do { __builtin_amdgcn_s_setprio(1); _Pragma("unroll") for (int m = 0; m < 4; ++m) _Pragma("unroll") for (int n = 0; n < 2; ++n) _Pragma("unroll") for (int k = 0; k < 2; ++k) \
;         acc[ai][bj][m][n] = __builtin_amdgcn_mfma_f32_16x16x32_bf16(Bt[n][k], At[m][k], acc[ai][bj][m][n], 0, 0, 0); __builtin_amdgcn_s_setprio(0); } while (0)
; #define PG8_BAR __builtin_amdgcn_s_barrier()
; template <class Epi, class Sched, bool ALIGN_EPI = false, bool SP2 = false>
; __device__ __forceinline__ void gemm_phase(PG8_LAS unsigned char* lds, const Gemm g, const Sched& S, const Epi& E) {
;     ...
;             if constexpr (SP2) {
;             PG8_LDB(B0, 0, 0); PG8_LDB(B1, 0, 1); PG8_SCHED; PG8_LDA(At, 0, 0); PG8_STAGE(PG8_SA(1, 1), a1 + hstep, voffA);
;             PG8_WAIT_V(8); PG8_WAIT_L(0); PG8_BAR; PG8_MMA(0, 0, At, B0); PG8_MMA(0, 1, At, B1); PG8_BAR; PG8_SCHED;
;             PG8_LDA(At, 0, 1); PG8_STAGE(PG8_SB(0, 0), b2, voffB); PG8_STAGE(PG8_SB(0, 1), b2 + hstep, voffB); PG8_STAGE(PG8_SA(0, 0), a2, voffA);
;             PG8_WAIT_V(8); PG8_WAIT_L(0); PG8_BAR; PG8_MMA(1, 0, At, B0); PG8_MMA(1, 1, At, B1); PG8_BAR; PG8_SCHED;
;             PG8_LDB(B0, 1, 0); PG8_LDB(B1, 1, 1); PG8_SCHED; PG8_LDA(At, 1, 0); PG8_STAGE(PG8_SA(0, 1), a2 + hstep, voffA);
;             PG8_WAIT_V(8); PG8_WAIT_L(0); PG8_BAR; PG8_MMA(0, 0, At, B0); PG8_MMA(0, 1, At, B1); PG8_BAR; PG8_SCHED;
;             PG8_LDA(At, 1, 1); PG8_STAGE(PG8_SB(1, 0), b3, voffB); PG8_STAGE(PG8_SB(1, 1), b3 + hstep, voffB); PG8_STAGE(PG8_SA(1, 0), a3, voffA);
;             PG8_WAIT_V(8); PG8_WAIT_L(0); PG8_BAR; PG8_MMA(1, 0, At, B0); PG8_MMA(1, 1, At, B1); PG8_BAR; PG8_SCHED;
	s_setprio 1
	s_waitcnt lgkmcnt(0)
	v_mfma_f32_16x16x32_bf16 v[126:129], v[154:157], v[188:191], v[126:129]
	v_mfma_f32_16x16x32_bf16 v[126:129], v[158:161], v[198:201], v[126:129]
	v_mfma_f32_16x16x32_bf16 v[110:113], v[154:157], v[202:205], v[110:113]
	v_mfma_f32_16x16x32_bf16 v[110:113], v[158:161], v[206:209], v[110:113]
	v_mfma_f32_16x16x32_bf16 v[94:97], v[154:157], v[210:213], v[94:97]
	v_mfma_f32_16x16x32_bf16 v[94:97], v[158:161], v[214:217], v[94:97]
	v_mfma_f32_16x16x32_bf16 v[78:81], v[154:157], v[218:221], v[78:81]
	v_mfma_f32_16x16x32_bf16 v[78:81], v[158:161], v[222:225], v[78:81]
	v_mfma_f32_16x16x32_bf16 v[122:125], v[162:165], v[188:191], v[122:125]
	v_mfma_f32_16x16x32_bf16 v[122:125], v[166:169], v[198:201], v[122:125]
	v_mfma_f32_16x16x32_bf16 v[106:109], v[162:165], v[202:205], v[106:109]
	v_mfma_f32_16x16x32_bf16 v[106:109], v[166:169], v[206:209], v[106:109]
	v_mfma_f32_16x16x32_bf16 v[90:93], v[162:165], v[210:213], v[90:93]
	v_mfma_f32_16x16x32_bf16 v[90:93], v[166:169], v[214:217], v[90:93]
	v_mfma_f32_16x16x32_bf16 v[74:77], v[162:165], v[218:221], v[74:77]
	v_mfma_f32_16x16x32_bf16 v[74:77], v[166:169], v[222:225], v[74:77]
	s_setprio 0
	s_setprio 1
	v_mfma_f32_16x16x32_bf16 v[118:121], v[170:173], v[188:191], v[118:121]
	v_mfma_f32_16x16x32_bf16 v[118:121], v[174:177], v[198:201], v[118:121]
	v_mfma_f32_16x16x32_bf16 v[102:105], v[170:173], v[202:205], v[102:105]
	v_mfma_f32_16x16x32_bf16 v[102:105], v[174:177], v[206:209], v[102:105]
	v_mfma_f32_16x16x32_bf16 v[86:89], v[170:173], v[210:213], v[86:89]
	v_mfma_f32_16x16x32_bf16 v[86:89], v[174:177], v[214:217], v[86:89]
	v_mfma_f32_16x16x32_bf16 v[70:73], v[170:173], v[218:221], v[70:73]
	v_mfma_f32_16x16x32_bf16 v[70:73], v[174:177], v[222:225], v[70:73]
	v_mfma_f32_16x16x32_bf16 v[114:117], v[180:183], v[188:191], v[114:117]
	v_mfma_f32_16x16x32_bf16 v[114:117], v[184:187], v[198:201], v[114:117]
	v_mfma_f32_16x16x32_bf16 v[98:101], v[180:183], v[202:205], v[98:101]
	v_mfma_f32_16x16x32_bf16 v[98:101], v[184:187], v[206:209], v[98:101]
	v_mfma_f32_16x16x32_bf16 v[82:85], v[180:183], v[210:213], v[82:85]
	v_mfma_f32_16x16x32_bf16 v[82:85], v[184:187], v[214:217], v[82:85]
	v_mfma_f32_16x16x32_bf16 v[66:69], v[180:183], v[218:221], v[66:69]
	v_mfma_f32_16x16x32_bf16 v[66:69], v[184:187], v[222:225], v[66:69]
	s_setprio 0
	s_barrier
	s_add_u32 s50, s48, 0x8000
	s_addc_u32 s51, s49, 0
	s_add_i32 s71, s71, s3
	v_lshl_add_u64 v[146:147], s[50:51], 0, v[132:133]
	s_mov_b32 m0, s71
	ds_read_b128 v[188:191], v151 offset:49152
	ds_read_b128 v[198:201], v151 offset:50176
	ds_read_b128 v[202:205], v151 offset:51200
	ds_read_b128 v[206:209], v151 offset:52224
	ds_read_b128 v[210:213], v151 offset:53248
	ds_read_b128 v[214:217], v151 offset:54272
	ds_read_b128 v[218:221], v151 offset:55296
	ds_read_b128 v[222:225], v151 offset:56320
	global_load_lds_dwordx4 v[146:147], off
	s_add_i32 m0, s71, 0x2000
	s_add_u32 s48, s48, 0xc000
	v_lshl_add_u64 v[146:147], s[50:51], 0, v[136:137]
	s_addc_u32 s49, s49, 0
	s_add_i32 s50, s72, s3
	global_load_lds_dwordx4 v[146:147], off
	v_lshl_add_u64 v[146:147], s[48:49], 0, v[132:133]
	s_mov_b32 m0, s50
	s_nop 0
	global_load_lds_dwordx4 v[146:147], off
	v_lshl_add_u64 v[146:147], s[48:49], 0, v[136:137]
	s_add_i32 m0, s50, 0x2000
	s_nop 0
	global_load_lds_dwordx4 v[146:147], off
	s_waitcnt vmcnt(6)
	s_waitcnt lgkmcnt(0)
	s_barrier
	s_setprio 1
	s_waitcnt lgkmcnt(0)
	v_mfma_f32_16x16x32_bf16 v[62:65], v[154:157], v[188:191], v[62:65]
	v_mfma_f32_16x16x32_bf16 v[62:65], v[158:161], v[198:201], v[62:65]
	v_mfma_f32_16x16x32_bf16 v[46:49], v[154:157], v[202:205], v[46:49]
	v_mfma_f32_16x16x32_bf16 v[46:49], v[158:161], v[206:209], v[46:49]
	v_mfma_f32_16x16x32_bf16 v[30:33], v[154:157], v[210:213], v[30:33]
	v_mfma_f32_16x16x32_bf16 v[30:33], v[158:161], v[214:217], v[30:33]
	v_mfma_f32_16x16x32_bf16 v[14:17], v[154:157], v[218:221], v[14:17]
	v_mfma_f32_16x16x32_bf16 v[14:17], v[158:161], v[222:225], v[14:17]
	v_mfma_f32_16x16x32_bf16 v[58:61], v[162:165], v[188:191], v[58:61]
	v_mfma_f32_16x16x32_bf16 v[58:61], v[166:169], v[198:201], v[58:61]
	v_mfma_f32_16x16x32_bf16 v[42:45], v[162:165], v[202:205], v[42:45]
	v_mfma_f32_16x16x32_bf16 v[42:45], v[166:169], v[206:209], v[42:45]
	v_mfma_f32_16x16x32_bf16 v[26:29], v[162:165], v[210:213], v[26:29]
	v_mfma_f32_16x16x32_bf16 v[26:29], v[166:169], v[214:217], v[26:29]
	v_mfma_f32_16x16x32_bf16 v[10:13], v[162:165], v[218:221], v[10:13]
	v_mfma_f32_16x16x32_bf16 v[10:13], v[166:169], v[222:225], v[10:13]
	s_setprio 0
	s_setprio 1
	v_mfma_f32_16x16x32_bf16 v[54:57], v[170:173], v[188:191], v[54:57]
	v_mfma_f32_16x16x32_bf16 v[54:57], v[174:177], v[198:201], v[54:57]
	v_mfma_f32_16x16x32_bf16 v[38:41], v[170:173], v[202:205], v[38:41]
	v_mfma_f32_16x16x32_bf16 v[38:41], v[174:177], v[206:209], v[38:41]
	v_mfma_f32_16x16x32_bf16 v[22:25], v[170:173], v[210:213], v[22:25]
	v_mfma_f32_16x16x32_bf16 v[22:25], v[174:177], v[214:217], v[22:25]
	v_mfma_f32_16x16x32_bf16 v[6:9], v[170:173], v[218:221], v[6:9]
	v_mfma_f32_16x16x32_bf16 v[6:9], v[174:177], v[222:225], v[6:9]
	v_mfma_f32_16x16x32_bf16 v[50:53], v[180:183], v[188:191], v[50:53]
	v_mfma_f32_16x16x32_bf16 v[50:53], v[184:187], v[198:201], v[50:53]
	v_mfma_f32_16x16x32_bf16 v[34:37], v[180:183], v[202:205], v[34:37]
	v_mfma_f32_16x16x32_bf16 v[34:37], v[184:187], v[206:209], v[34:37]
	v_mfma_f32_16x16x32_bf16 v[18:21], v[180:183], v[210:213], v[18:21]
	v_mfma_f32_16x16x32_bf16 v[18:21], v[184:187], v[214:217], v[18:21]
	v_mfma_f32_16x16x32_bf16 v[2:5], v[180:183], v[218:221], v[2:5]
	v_mfma_f32_16x16x32_bf16 v[2:5], v[184:187], v[222:225], v[2:5]
	s_setprio 0
	s_barrier
	s_add_i32 s70, s70, 2
	s_add_u32 s44, s44, 0x10000
	s_addc_u32 s45, s45, 0
	s_add_u32 s68, s68, 0x10000
	s_addc_u32 s69, s69, 0
	s_cmp_gt_u32 s70, 61
	s_cbranch_scc0 .LBB0_757
	s_and_b64 vcc, exec, s[12:13]
	s_cbranch_vccz .LBB0_760
	s_barrier

; #define PG8_STAGE(bufoff, gbase, voff) do { _Pragma("unroll") for (int _i = 0; _i < 2; ++_i) \
;         __builtin_amdgcn_global_load_lds((const unsigned*)((const char*)(gbase) + (voff)[_i]), (PG8_LAS unsigned*)(lds + (bufoff) + ldsw + _i * 8192), 16, 0, 0); } while (0)
; #define PG8_LDA(dst, b, h) do { _Pragma("unroll") for (int m = 0; m < 4; ++m) _Pragma("unroll") for (int k = 0; k < 2; ++k) dst[m][k] = *(const PG8_LAS bf16x8*)(lds + PG8_SA(b, h) + aoff + m * 2048 + k * 1024); } while (0)
; #define PG8_LDB(dst, b, h) do { _Pragma("unroll") for (int n = 0; n < 2; ++n) _Pragma("unroll") for (int k = 0; k < 2; ++k) dst[n][k] = *(const PG8_LAS bf16x8*)(lds + PG8_SB(b, h) + boff + n * 2048 + k * 1024); } while (0)
; #define PG8_MMA(ai, bj, At, Bt) do { __builtin_amdgcn_s_setprio(1); _Pragma("unroll") for (int m = 0; m < 4; ++m) _Pragma("unroll") for (int n = 0; n < 2; ++n) _Pragma("unroll") for (int k = 0; k < 2; ++k) \
;         acc[ai][bj][m][n] = __builtin_amdgcn_mfma_f32_16x16x32_bf16(Bt[n][k], At[m][k], acc[ai][bj][m][n], 0, 0, 0); __builtin_amdgcn_s_setprio(0); } while (0)
; #define PG8_WAIT_V(n) asm volatile("s_waitcnt vmcnt(" #n ")" ::: "memory")
; #define PG8_WAIT_L(n) asm volatile("s_waitcnt lgkmcnt(" #n ")" ::: "memory")
; template <class Epi, class Sched, bool ALIGN_EPI = false, bool SP2 = false>
; __device__ __forceinline__ void gemm_phase(PG8_LAS unsigned char* lds, const Gemm g, const Sched& S, const Epi& E) {
;     ...
;         for (; t < tend; t += 2) {
;             const bool last = (t == nt - 2);
;             const char* a1 = cA + (size_t)(t + 1) * kstep;
;             const char* a2 = last ? nA : cA + (size_t)(t + 2) * kstep; const char* b2 = last ? nB : cB + (size_t)(t + 2) * kstep;
;             const char* a3 = a2 + kstep; const char* b3 = b2 + kstep;
;             if (last && has_next) S.a_ready(nxt);
;             if constexpr (SP2) {
;             PG8_LDB(B0, 0, 0); PG8_LDB(B1, 0, 1); PG8_SCHED; PG8_LDA(At, 0, 0); PG8_STAGE(PG8_SA(1, 1), a1 + hstep, voffA);
;             PG8_WAIT_V(8); PG8_WAIT_L(0); PG8_BAR; PG8_MMA(0, 0, At, B0); PG8_MMA(0, 1, At, B1); PG8_BAR; PG8_SCHED;
;             PG8_LDA(At, 0, 1); PG8_STAGE(PG8_SB(0, 0), b2, voffB); PG8_STAGE(PG8_SB(0, 1), b2 + hstep, voffB); PG8_STAGE(PG8_SA(0, 0), a2, voffA);
;             PG8_WAIT_V(8); PG8_WAIT_L(0); PG8_BAR; PG8_MMA(1, 0, At, B0); PG8_MMA(1, 1, At, B1); PG8_BAR; PG8_SCHED;
.LBB0_840:
	ds_read_b128 v[148:151], v153
	ds_read_b128 v[158:161], v153 offset:1024
	ds_read_b128 v[162:165], v153 offset:2048
	ds_read_b128 v[166:169], v153 offset:3072
	ds_read_b128 v[170:173], v154
	ds_read_b128 v[174:177], v154 offset:1024
	ds_read_b128 v[180:183], v154 offset:2048
	ds_read_b128 v[184:187], v154 offset:3072
	s_add_u32 s42, s40, 0x4000
	s_addc_u32 s43, s41, 0
	s_cmp_eq_u32 s69, 60
	s_cselect_b32 s46, s65, s42
	s_cselect_b32 s47, s23, s43
	s_cselect_b32 s44, s66, s67
	s_cselect_b32 s45, s17, s68
	s_add_u32 s42, s46, 0x8000
	s_addc_u32 s43, s47, 0
	s_sub_u32 s42, s40, 0x4000
	s_subb_u32 s43, s41, 0
	v_lshl_add_u64 v[226:227], s[42:43], 0, v[130:131]
	s_mov_b32 m0, s50
	s_nop 0
	global_load_lds_dwordx4 v[226:227], off
	v_lshl_add_u64 v[226:227], s[42:43], 0, v[134:135]
	s_mov_b32 m0, s51
	s_nop 0
	global_load_lds_dwordx4 v[226:227], off
	v_lshl_add_u64 v[226:227], s[40:41], 0, v[140:141]
	s_add_i32 m0, s28, 0xc000
	ds_read_b128 v[188:191], v155
	ds_read_b128 v[198:201], v155 offset:1024
	ds_read_b128 v[202:205], v155 offset:2048
	ds_read_b128 v[206:209], v155 offset:3072
	ds_read_b128 v[210:213], v155 offset:4096
	ds_read_b128 v[214:217], v155 offset:5120
	ds_read_b128 v[218:221], v155 offset:6144
	ds_read_b128 v[222:225], v155 offset:7168
	global_load_lds_dwordx4 v[226:227], off
	v_lshl_add_u64 v[226:227], s[40:41], 0, v[142:143]
	s_add_i32 m0, s28, 0xe000
	s_nop 0
	global_load_lds_dwordx4 v[226:227], off
	s_waitcnt vmcnt(8)
	s_waitcnt lgkmcnt(0)
	s_barrier
	s_setprio 1
	s_waitcnt lgkmcnt(0)
	v_mfma_f32_16x16x32_bf16 v[126:129], v[148:151], v[188:191], v[126:129]
	v_mfma_f32_16x16x32_bf16 v[126:129], v[158:161], v[198:201], v[126:129]
	v_mfma_f32_16x16x32_bf16 v[110:113], v[148:151], v[202:205], v[110:113]
	v_mfma_f32_16x16x32_bf16 v[110:113], v[158:161], v[206:209], v[110:113]
	v_mfma_f32_16x16x32_bf16 v[94:97], v[148:151], v[210:213], v[94:97]
	v_mfma_f32_16x16x32_bf16 v[94:97], v[158:161], v[214:217], v[94:97]
	v_mfma_f32_16x16x32_bf16 v[78:81], v[148:151], v[218:221], v[78:81]
	v_mfma_f32_16x16x32_bf16 v[78:81], v[158:161], v[222:225], v[78:81]
	v_mfma_f32_16x16x32_bf16 v[122:125], v[162:165], v[188:191], v[122:125]
	v_mfma_f32_16x16x32_bf16 v[122:125], v[166:169], v[198:201], v[122:125]
	v_mfma_f32_16x16x32_bf16 v[106:109], v[162:165], v[202:205], v[106:109]
	v_mfma_f32_16x16x32_bf16 v[106:109], v[166:169], v[206:209], v[106:109]
	v_mfma_f32_16x16x32_bf16 v[90:93], v[162:165], v[210:213], v[90:93]
	v_mfma_f32_16x16x32_bf16 v[90:93], v[166:169], v[214:217], v[90:93]
	v_mfma_f32_16x16x32_bf16 v[74:77], v[162:165], v[218:221], v[74:77]
	v_mfma_f32_16x16x32_bf16 v[74:77], v[166:169], v[222:225], v[74:77]
	s_setprio 0
	s_setprio 1
	v_mfma_f32_16x16x32_bf16 v[118:121], v[170:173], v[188:191], v[118:121]
	v_mfma_f32_16x16x32_bf16 v[118:121], v[174:177], v[198:201], v[118:121]
	v_mfma_f32_16x16x32_bf16 v[102:105], v[170:173], v[202:205], v[102:105]
	v_mfma_f32_16x16x32_bf16 v[102:105], v[174:177], v[206:209], v[102:105]
	v_mfma_f32_16x16x32_bf16 v[86:89], v[170:173], v[210:213], v[86:89]
	v_mfma_f32_16x16x32_bf16 v[86:89], v[174:177], v[214:217], v[86:89]
	v_mfma_f32_16x16x32_bf16 v[70:73], v[170:173], v[218:221], v[70:73]
	v_mfma_f32_16x16x32_bf16 v[70:73], v[174:177], v[222:225], v[70:73]
	v_mfma_f32_16x16x32_bf16 v[114:117], v[180:183], v[188:191], v[114:117]
	v_mfma_f32_16x16x32_bf16 v[114:117], v[184:187], v[198:201], v[114:117]
	v_mfma_f32_16x16x32_bf16 v[98:101], v[180:183], v[202:205], v[98:101]
	v_mfma_f32_16x16x32_bf16 v[98:101], v[184:187], v[206:209], v[98:101]
	v_mfma_f32_16x16x32_bf16 v[82:85], v[180:183], v[210:213], v[82:85]
	v_mfma_f32_16x16x32_bf16 v[82:85], v[184:187], v[214:217], v[82:85]
	v_mfma_f32_16x16x32_bf16 v[66:69], v[180:183], v[218:221], v[66:69]
	v_mfma_f32_16x16x32_bf16 v[66:69], v[184:187], v[222:225], v[66:69]
	s_setprio 0
	s_barrier
	s_add_i32 s70, s56, s3
	v_lshl_add_u64 v[226:227], s[44:45], 0, v[132:133]
	s_mov_b32 m0, s70
	ds_read_b128 v[188:191], v155 offset:16384
	ds_read_b128 v[198:201], v155 offset:17408
	ds_read_b128 v[202:205], v155 offset:18432
	ds_read_b128 v[206:209], v155 offset:19456
	ds_read_b128 v[210:213], v155 offset:20480
	ds_read_b128 v[214:217], v155 offset:21504
	ds_read_b128 v[218:221], v155 offset:22528
	ds_read_b128 v[222:225], v155 offset:23552
	global_load_lds_dwordx4 v[226:227], off
	s_add_i32 m0, s70, 0x2000
	s_add_u32 s70, s44, 0x4000
	v_lshl_add_u64 v[226:227], s[44:45], 0, v[136:137]
	s_addc_u32 s71, s45, 0
	s_add_i32 s72, s57, s3
	global_load_lds_dwordx4 v[226:227], off
	v_lshl_add_u64 v[226:227], s[70:71], 0, v[132:133]
	s_mov_b32 m0, s72
	s_nop 0
	global_load_lds_dwordx4 v[226:227], off
	v_lshl_add_u64 v[226:227], s[70:71], 0, v[136:137]
	s_add_i32 m0, s72, 0x2000
	s_nop 0
	global_load_lds_dwordx4 v[226:227], off
	s_waitcnt vmcnt(6)
	s_waitcnt lgkmcnt(0)
	s_barrier
; #define PG8_STAGE(bufoff, gbase, voff) do { _Pragma("unroll") for (int _i = 0; _i < 2; ++_i) \
;         __builtin_amdgcn_global_load_lds((const unsigned*)((const char*)(gbase) + (voff)[_i]), (PG8_LAS unsigned*)(lds + (bufoff) + ldsw + _i * 8192), 16, 0, 0); } while (0)
; #define PG8_LDA(dst, b, h) do { _Pragma("unroll") for (int m = 0; m < 4; ++m) _Pragma("unroll") for (int k = 0; k < 2; ++k) dst[m][k] = *(const PG8_LAS bf16x8*)(lds + PG8_SA(b, h) + aoff + m * 2048 + k * 1024); } while (0)
; #define PG8_LDB(dst, b, h) do { _Pragma("unroll") for (int n = 0; n < 2; ++n) _Pragma("unroll") for (int k = 0; k < 2; ++k) dst[n][k] = *(const PG8_LAS bf16x8*)(lds + PG8_SB(b, h) + boff + n * 2048 + k * 1024); } while (0)
; #define PG8_MMA(ai, bj, At, Bt) do { __builtin_amdgcn_s_setprio(1); _Pragma("unroll") for (int m = 0; m < 4; ++m) _Pragma("unroll") for (int n = 0; n < 2; ++n) _Pragma("unroll") for (int k = 0; k < 2; ++k) \
;         acc[ai][bj][m][n] = __builtin_amdgcn_mfma_f32_16x16x32_bf16(Bt[n][k], At[m][k], acc[ai][bj][m][n], 0, 0, 0); __builtin_amdgcn_s_setprio(0); } while (0)
; #define PG8_WAIT_V(n) asm volatile("s_waitcnt vmcnt(" #n ")" ::: "memory")
; #define PG8_WAIT_L(n) asm volatile("s_waitcnt lgkmcnt(" #n ")" ::: "memory")
; #define PG8_BAR __builtin_amdgcn_s_barrier()
; #define PG8_SCHED __builtin_amdgcn_sched_barrier(0)
; template <class Epi, class Sched, bool ALIGN_EPI = false, bool SP2 = false>
; __device__ __forceinline__ void gemm_phase(PG8_LAS unsigned char* lds, const Gemm g, const Sched& S, const Epi& E) {
;     ...
;             PG8_WAIT_V(8); PG8_WAIT_L(0); PG8_BAR; PG8_MMA(1, 0, At, B0); PG8_MMA(1, 1, At, B1); PG8_BAR; PG8_SCHED;
;             PG8_LDB(B0, 1, 0); PG8_LDB(B1, 1, 1); PG8_SCHED; PG8_LDA(At, 1, 0); PG8_STAGE(PG8_SA(0, 1), a2 + hstep, voffA);
;             PG8_WAIT_V(8); PG8_WAIT_L(0); PG8_BAR; PG8_MMA(0, 0, At, B0); PG8_MMA(0, 1, At, B1); PG8_BAR; PG8_SCHED;
	s_setprio 1
	s_waitcnt lgkmcnt(0)
	v_mfma_f32_16x16x32_bf16 v[62:65], v[148:151], v[188:191], v[62:65]
	v_mfma_f32_16x16x32_bf16 v[62:65], v[158:161], v[198:201], v[62:65]
	v_mfma_f32_16x16x32_bf16 v[46:49], v[148:151], v[202:205], v[46:49]
	v_mfma_f32_16x16x32_bf16 v[46:49], v[158:161], v[206:209], v[46:49]
	v_mfma_f32_16x16x32_bf16 v[30:33], v[148:151], v[210:213], v[30:33]
	v_mfma_f32_16x16x32_bf16 v[30:33], v[158:161], v[214:217], v[30:33]
	v_mfma_f32_16x16x32_bf16 v[14:17], v[148:151], v[218:221], v[14:17]
	v_mfma_f32_16x16x32_bf16 v[14:17], v[158:161], v[222:225], v[14:17]
	v_mfma_f32_16x16x32_bf16 v[58:61], v[162:165], v[188:191], v[58:61]
	v_mfma_f32_16x16x32_bf16 v[58:61], v[166:169], v[198:201], v[58:61]
	v_mfma_f32_16x16x32_bf16 v[42:45], v[162:165], v[202:205], v[42:45]
	v_mfma_f32_16x16x32_bf16 v[42:45], v[166:169], v[206:209], v[42:45]
	v_mfma_f32_16x16x32_bf16 v[26:29], v[162:165], v[210:213], v[26:29]
	v_mfma_f32_16x16x32_bf16 v[26:29], v[166:169], v[214:217], v[26:29]
	v_mfma_f32_16x16x32_bf16 v[10:13], v[162:165], v[218:221], v[10:13]
	v_mfma_f32_16x16x32_bf16 v[10:13], v[166:169], v[222:225], v[10:13]
	s_setprio 0
	s_setprio 1
	v_mfma_f32_16x16x32_bf16 v[54:57], v[170:173], v[188:191], v[54:57]
	v_mfma_f32_16x16x32_bf16 v[54:57], v[174:177], v[198:201], v[54:57]
	v_mfma_f32_16x16x32_bf16 v[38:41], v[170:173], v[202:205], v[38:41]
	v_mfma_f32_16x16x32_bf16 v[38:41], v[174:177], v[206:209], v[38:41]
	v_mfma_f32_16x16x32_bf16 v[22:25], v[170:173], v[210:213], v[22:25]
	v_mfma_f32_16x16x32_bf16 v[22:25], v[174:177], v[214:217], v[22:25]
	v_mfma_f32_16x16x32_bf16 v[6:9], v[170:173], v[218:221], v[6:9]
	v_mfma_f32_16x16x32_bf16 v[6:9], v[174:177], v[222:225], v[6:9]
	v_mfma_f32_16x16x32_bf16 v[50:53], v[180:183], v[188:191], v[50:53]
	v_mfma_f32_16x16x32_bf16 v[50:53], v[184:187], v[198:201], v[50:53]
	v_mfma_f32_16x16x32_bf16 v[34:37], v[180:183], v[202:205], v[34:37]
	v_mfma_f32_16x16x32_bf16 v[34:37], v[184:187], v[206:209], v[34:37]
	v_mfma_f32_16x16x32_bf16 v[18:21], v[180:183], v[210:213], v[18:21]
	v_mfma_f32_16x16x32_bf16 v[18:21], v[184:187], v[214:217], v[18:21]
	v_mfma_f32_16x16x32_bf16 v[2:5], v[180:183], v[218:221], v[2:5]
	v_mfma_f32_16x16x32_bf16 v[2:5], v[184:187], v[222:225], v[2:5]
	s_setprio 0
	s_barrier
	s_add_i32 s70, 0, 0x18000
	v_add_u32_e32 v138, s70, v1
	s_add_i32 s71, 0, 0x1c000
	ds_read_b128 v[148:151], v138
	ds_read_b128 v[158:161], v138 offset:1024
	ds_read_b128 v[162:165], v138 offset:2048
	ds_read_b128 v[166:169], v138 offset:3072
	v_add_u32_e32 v138, s71, v1
	ds_read_b128 v[170:173], v138
	ds_read_b128 v[174:177], v138 offset:1024
	ds_read_b128 v[180:183], v138 offset:2048
	ds_read_b128 v[184:187], v138 offset:3072
	v_lshl_add_u64 v[226:227], s[46:47], 0, v[130:131]
	s_mov_b32 m0, s28
	s_nop 0
	global_load_lds_dwordx4 v[226:227], off
	v_lshl_add_u64 v[226:227], s[46:47], 0, v[134:135]
	s_mov_b32 m0, s29
	s_nop 0
	global_load_lds_dwordx4 v[226:227], off
	s_add_u32 s46, s46, 0x4000
	s_addc_u32 s47, s47, 0
	s_mov_b32 m0, s30
	v_lshl_add_u64 v[226:227], s[46:47], 0, v[130:131]
	ds_read_b128 v[188:191], v155 offset:32768
	ds_read_b128 v[198:201], v155 offset:33792
	ds_read_b128 v[202:205], v155 offset:34816
	ds_read_b128 v[206:209], v155 offset:35840
	ds_read_b128 v[210:213], v155 offset:36864
	ds_read_b128 v[214:217], v155 offset:37888
	ds_read_b128 v[218:221], v155 offset:38912
	ds_read_b128 v[222:225], v155 offset:39936
	global_load_lds_dwordx4 v[226:227], off
	v_lshl_add_u64 v[226:227], s[46:47], 0, v[134:135]
	s_mov_b32 m0, s31
	s_nop 0
	global_load_lds_dwordx4 v[226:227], off
	s_waitcnt vmcnt(8)
	s_waitcnt lgkmcnt(0)
	s_barrier
; #define PG8_STAGE(bufoff, gbase, voff) do { _Pragma("unroll") for (int _i = 0; _i < 2; ++_i) \
;         __builtin_amdgcn_global_load_lds((const unsigned*)((const char*)(gbase) + (voff)[_i]), (PG8_LAS unsigned*)(lds + (bufoff) + ldsw + _i * 8192), 16, 0, 0); } while (0)
; #define PG8_LDA(dst, b, h) do { _Pragma("unroll") for (int m = 0; m < 4; ++m) _Pragma("unroll") for (int k = 0; k < 2; ++k) dst[m][k] = *(const PG8_LAS bf16x8*)(lds + PG8_SA(b, h) + aoff + m * 2048 + k * 1024); } while (0)
; #define PG8_MMA(ai, bj, At, Bt) do { __builtin_amdgcn_s_setprio(1); _Pragma("unroll") for (int m = 0; m < 4; ++m) _Pragma("unroll") for (int n = 0; n < 2; ++n) _Pragma("unroll") for (int k = 0; k < 2; ++k) \
;         acc[ai][bj][m][n] = __builtin_amdgcn_mfma_f32_16x16x32_bf16(Bt[n][k], At[m][k], acc[ai][bj][m][n], 0, 0, 0); __builtin_amdgcn_s_setprio(0); } while (0)
; #define PG8_WAIT_V(n) asm volatile("s_waitcnt vmcnt(" #n ")" ::: "memory")
; #define PG8_WAIT_L(n) asm volatile("s_waitcnt lgkmcnt(" #n ")" ::: "memory")
; #define PG8_BAR __builtin_amdgcn_s_barrier()
; #define PG8_SCHED __builtin_amdgcn_sched_barrier(0)
; template <class Epi, class Sched, bool ALIGN_EPI = false, bool SP2 = false>
; __device__ __forceinline__ void gemm_phase(PG8_LAS unsigned char* lds, const Gemm g, const Sched& S, const Epi& E) {
;     ...
;             PG8_WAIT_V(8); PG8_WAIT_L(0); PG8_BAR; PG8_MMA(0, 0, At, B0); PG8_MMA(0, 1, At, B1); PG8_BAR; PG8_SCHED;
;             PG8_LDA(At, 1, 1); PG8_STAGE(PG8_SB(1, 0), b3, voffB); PG8_STAGE(PG8_SB(1, 1), b3 + hstep, voffB); PG8_STAGE(PG8_SA(1, 0), a3, voffA);
;             PG8_WAIT_V(8); PG8_WAIT_L(0); PG8_BAR; PG8_MMA(1, 0, At, B0); PG8_MMA(1, 1, At, B1); PG8_BAR; PG8_SCHED;
;     ...
;         }
;         if constexpr (Epi::HAS_MID) { if (seg == 0) E.mid(acc, cur, wr, wc, fr, fq); }
;         }
;         if constexpr (ALIGN_EPI) { if (wr == 0) PG8_BAR; }
	s_setprio 1
	s_waitcnt lgkmcnt(0)
	v_mfma_f32_16x16x32_bf16 v[126:129], v[148:151], v[188:191], v[126:129]
	v_mfma_f32_16x16x32_bf16 v[126:129], v[158:161], v[198:201], v[126:129]
	v_mfma_f32_16x16x32_bf16 v[110:113], v[148:151], v[202:205], v[110:113]
	v_mfma_f32_16x16x32_bf16 v[110:113], v[158:161], v[206:209], v[110:113]
	v_mfma_f32_16x16x32_bf16 v[94:97], v[148:151], v[210:213], v[94:97]
	v_mfma_f32_16x16x32_bf16 v[94:97], v[158:161], v[214:217], v[94:97]
	v_mfma_f32_16x16x32_bf16 v[78:81], v[148:151], v[218:221], v[78:81]
	v_mfma_f32_16x16x32_bf16 v[78:81], v[158:161], v[222:225], v[78:81]
	v_mfma_f32_16x16x32_bf16 v[122:125], v[162:165], v[188:191], v[122:125]
	v_mfma_f32_16x16x32_bf16 v[122:125], v[166:169], v[198:201], v[122:125]
	v_mfma_f32_16x16x32_bf16 v[106:109], v[162:165], v[202:205], v[106:109]
	v_mfma_f32_16x16x32_bf16 v[106:109], v[166:169], v[206:209], v[106:109]
	v_mfma_f32_16x16x32_bf16 v[90:93], v[162:165], v[210:213], v[90:93]
	v_mfma_f32_16x16x32_bf16 v[90:93], v[166:169], v[214:217], v[90:93]
	v_mfma_f32_16x16x32_bf16 v[74:77], v[162:165], v[218:221], v[74:77]
	v_mfma_f32_16x16x32_bf16 v[74:77], v[166:169], v[222:225], v[74:77]
	s_setprio 0
	s_setprio 1
	v_mfma_f32_16x16x32_bf16 v[118:121], v[170:173], v[188:191], v[118:121]
	v_mfma_f32_16x16x32_bf16 v[118:121], v[174:177], v[198:201], v[118:121]
	v_mfma_f32_16x16x32_bf16 v[102:105], v[170:173], v[202:205], v[102:105]
	v_mfma_f32_16x16x32_bf16 v[102:105], v[174:177], v[206:209], v[102:105]
	v_mfma_f32_16x16x32_bf16 v[86:89], v[170:173], v[210:213], v[86:89]
	v_mfma_f32_16x16x32_bf16 v[86:89], v[174:177], v[214:217], v[86:89]
	v_mfma_f32_16x16x32_bf16 v[70:73], v[170:173], v[218:221], v[70:73]
	v_mfma_f32_16x16x32_bf16 v[70:73], v[174:177], v[222:225], v[70:73]
	v_mfma_f32_16x16x32_bf16 v[114:117], v[180:183], v[188:191], v[114:117]
	v_mfma_f32_16x16x32_bf16 v[114:117], v[184:187], v[198:201], v[114:117]
	v_mfma_f32_16x16x32_bf16 v[98:101], v[180:183], v[202:205], v[98:101]
	v_mfma_f32_16x16x32_bf16 v[98:101], v[184:187], v[206:209], v[98:101]
	v_mfma_f32_16x16x32_bf16 v[82:85], v[180:183], v[210:213], v[82:85]
	v_mfma_f32_16x16x32_bf16 v[82:85], v[184:187], v[214:217], v[82:85]
	v_mfma_f32_16x16x32_bf16 v[66:69], v[180:183], v[218:221], v[66:69]
	v_mfma_f32_16x16x32_bf16 v[66:69], v[184:187], v[222:225], v[66:69]
	s_setprio 0
	s_barrier
	s_add_u32 s46, s44, 0x8000
	s_addc_u32 s47, s45, 0
	s_add_i32 s70, s70, s3
	v_lshl_add_u64 v[226:227], s[46:47], 0, v[132:133]
	s_mov_b32 m0, s70
	ds_read_b128 v[188:191], v155 offset:49152
	ds_read_b128 v[198:201], v155 offset:50176
	ds_read_b128 v[202:205], v155 offset:51200
	ds_read_b128 v[206:209], v155 offset:52224
	ds_read_b128 v[210:213], v155 offset:53248
	ds_read_b128 v[214:217], v155 offset:54272
	ds_read_b128 v[218:221], v155 offset:55296
	ds_read_b128 v[222:225], v155 offset:56320
	global_load_lds_dwordx4 v[226:227], off
	s_add_i32 m0, s70, 0x2000
	s_add_u32 s44, s44, 0xc000
	v_lshl_add_u64 v[226:227], s[46:47], 0, v[136:137]
	s_addc_u32 s45, s45, 0
	s_add_i32 s46, s71, s3
	global_load_lds_dwordx4 v[226:227], off
	v_lshl_add_u64 v[226:227], s[44:45], 0, v[132:133]
	s_mov_b32 m0, s46
	s_nop 0
	global_load_lds_dwordx4 v[226:227], off
	v_lshl_add_u64 v[226:227], s[44:45], 0, v[136:137]
	s_add_i32 m0, s46, 0x2000
	s_nop 0
	global_load_lds_dwordx4 v[226:227], off
	s_waitcnt vmcnt(6)
	s_waitcnt lgkmcnt(0)
	s_barrier
	s_setprio 1
	s_waitcnt lgkmcnt(0)
	v_mfma_f32_16x16x32_bf16 v[62:65], v[148:151], v[188:191], v[62:65]
	v_mfma_f32_16x16x32_bf16 v[62:65], v[158:161], v[198:201], v[62:65]
	v_mfma_f32_16x16x32_bf16 v[46:49], v[148:151], v[202:205], v[46:49]
	v_mfma_f32_16x16x32_bf16 v[46:49], v[158:161], v[206:209], v[46:49]
	v_mfma_f32_16x16x32_bf16 v[30:33], v[148:151], v[210:213], v[30:33]
	v_mfma_f32_16x16x32_bf16 v[30:33], v[158:161], v[214:217], v[30:33]
	v_mfma_f32_16x16x32_bf16 v[14:17], v[148:151], v[218:221], v[14:17]
	v_mfma_f32_16x16x32_bf16 v[14:17], v[158:161], v[222:225], v[14:17]
	v_mfma_f32_16x16x32_bf16 v[58:61], v[162:165], v[188:191], v[58:61]
	v_mfma_f32_16x16x32_bf16 v[58:61], v[166:169], v[198:201], v[58:61]
	v_mfma_f32_16x16x32_bf16 v[42:45], v[162:165], v[202:205], v[42:45]
	v_mfma_f32_16x16x32_bf16 v[42:45], v[166:169], v[206:209], v[42:45]
	v_mfma_f32_16x16x32_bf16 v[26:29], v[162:165], v[210:213], v[26:29]
	v_mfma_f32_16x16x32_bf16 v[26:29], v[166:169], v[214:217], v[26:29]
	v_mfma_f32_16x16x32_bf16 v[10:13], v[162:165], v[218:221], v[10:13]
	v_mfma_f32_16x16x32_bf16 v[10:13], v[166:169], v[222:225], v[10:13]
	s_setprio 0
	s_setprio 1
	v_mfma_f32_16x16x32_bf16 v[54:57], v[170:173], v[188:191], v[54:57]
	v_mfma_f32_16x16x32_bf16 v[54:57], v[174:177], v[198:201], v[54:57]
	v_mfma_f32_16x16x32_bf16 v[38:41], v[170:173], v[202:205], v[38:41]
	v_mfma_f32_16x16x32_bf16 v[38:41], v[174:177], v[206:209], v[38:41]
	v_mfma_f32_16x16x32_bf16 v[22:25], v[170:173], v[210:213], v[22:25]
	v_mfma_f32_16x16x32_bf16 v[22:25], v[174:177], v[214:217], v[22:25]
	v_mfma_f32_16x16x32_bf16 v[6:9], v[170:173], v[218:221], v[6:9]
	v_mfma_f32_16x16x32_bf16 v[6:9], v[174:177], v[222:225], v[6:9]
	v_mfma_f32_16x16x32_bf16 v[50:53], v[180:183], v[188:191], v[50:53]
	v_mfma_f32_16x16x32_bf16 v[50:53], v[184:187], v[198:201], v[50:53]
	v_mfma_f32_16x16x32_bf16 v[34:37], v[180:183], v[202:205], v[34:37]
	v_mfma_f32_16x16x32_bf16 v[34:37], v[184:187], v[206:209], v[34:37]
	v_mfma_f32_16x16x32_bf16 v[18:21], v[180:183], v[210:213], v[18:21]
	v_mfma_f32_16x16x32_bf16 v[18:21], v[184:187], v[214:217], v[18:21]
	v_mfma_f32_16x16x32_bf16 v[2:5], v[180:183], v[218:221], v[2:5]
	v_mfma_f32_16x16x32_bf16 v[2:5], v[184:187], v[222:225], v[2:5]
	s_setprio 0
	s_barrier
	s_add_i32 s69, s69, 2
	s_add_u32 s40, s40, 0x10000
	s_addc_u32 s41, s41, 0
	s_add_u32 s67, s67, 0x10000
	s_addc_u32 s68, s68, 0
	s_cmp_gt_u32 s69, 61
	s_cbranch_scc0 .LBB0_840
	s_and_b64 vcc, exec, s[14:15]
	s_cbranch_vccz .LBB0_843
	s_barrier

; #define PG8_STAGE(bufoff, gbase, voff) do { _Pragma("unroll") for (int _i = 0; _i < 2; ++_i) \
;         __builtin_amdgcn_global_load_lds((const unsigned*)((const char*)(gbase) + (voff)[_i]), (PG8_LAS unsigned*)(lds + (bufoff) + ldsw + _i * 8192), 16, 0, 0); } while (0)
; #define PG8_LDA(dst, b, h) do { _Pragma("unroll") for (int m = 0; m < 4; ++m) _Pragma("unroll") for (int k = 0; k < 2; ++k) dst[m][k] = *(const PG8_LAS bf16x8*)(lds + PG8_SA(b, h) + aoff + m * 2048 + k * 1024); } while (0)
; #define PG8_LDB(dst, b, h) do { _Pragma("unroll") for (int n = 0; n < 2; ++n) _Pragma("unroll") for (int k = 0; k < 2; ++k) dst[n][k] = *(const PG8_LAS bf16x8*)(lds + PG8_SB(b, h) + boff + n * 2048 + k * 1024); } while (0)
; #define PG8_MMA(ai, bj, At, Bt) do { __builtin_amdgcn_s_setprio(1); _Pragma("unroll") for (int m = 0; m < 4; ++m) _Pragma("unroll") for (int n = 0; n < 2; ++n) _Pragma("unroll") for (int k = 0; k < 2; ++k) \
;         acc[ai][bj][m][n] = __builtin_amdgcn_mfma_f32_16x16x32_bf16(Bt[n][k], At[m][k], acc[ai][bj][m][n], 0, 0, 0); __builtin_amdgcn_s_setprio(0); } while (0)
; #define PG8_WAIT_V(n) asm volatile("s_waitcnt vmcnt(" #n ")" ::: "memory")
; #define PG8_WAIT_L(n) asm volatile("s_waitcnt lgkmcnt(" #n ")" ::: "memory")
; template <class Epi, class Sched, bool ALIGN_EPI = false, bool SP2 = false>
; __device__ __forceinline__ void gemm_phase(PG8_LAS unsigned char* lds, const Gemm g, const Sched& S, const Epi& E) {
;     ...
;         for (; t < tend; t += 2) {
;             const bool last = (t == nt - 2);
;             const char* a1 = cA + (size_t)(t + 1) * kstep;
;             const char* a2 = last ? nA : cA + (size_t)(t + 2) * kstep; const char* b2 = last ? nB : cB + (size_t)(t + 2) * kstep;
;             const char* a3 = a2 + kstep; const char* b3 = b2 + kstep;
;             if (last && has_next) S.a_ready(nxt);
;             if constexpr (SP2) {
;             PG8_LDB(B0, 0, 0); PG8_LDB(B1, 0, 1); PG8_SCHED; PG8_LDA(At, 0, 0); PG8_STAGE(PG8_SA(1, 1), a1 + hstep, voffA);
;             PG8_WAIT_V(8); PG8_WAIT_L(0); PG8_BAR; PG8_MMA(0, 0, At, B0); PG8_MMA(0, 1, At, B1); PG8_BAR; PG8_SCHED;
;             PG8_LDA(At, 0, 1); PG8_STAGE(PG8_SB(0, 0), b2, voffB); PG8_STAGE(PG8_SB(0, 1), b2 + hstep, voffB); PG8_STAGE(PG8_SA(0, 0), a2, voffA);
;             PG8_WAIT_V(8); PG8_WAIT_L(0); PG8_BAR; PG8_MMA(1, 0, At, B0); PG8_MMA(1, 1, At, B1); PG8_BAR; PG8_SCHED;
.LBB0_939:
	s_or_b32 s24, s59, 1
	s_lshl_b64 s[62:63], s[24:25], 15
	s_add_i32 s24, s59, 2
	ds_read_b128 v[156:159], v193
	ds_read_b128 v[160:163], v193 offset:1024
	ds_read_b128 v[196:199], v193 offset:2048
	ds_read_b128 v[200:203], v193 offset:3072
	ds_read_b128 v[204:207], v194
	ds_read_b128 v[208:211], v194 offset:1024
	ds_read_b128 v[212:215], v194 offset:2048
	ds_read_b128 v[216:219], v194 offset:3072
	s_lshl_b64 s[8:9], s[24:25], 15
	s_add_u32 s44, s6, s8
	s_addc_u32 s45, s7, s9
	s_cmpk_eq_i32 s59, 0xaa
	s_cselect_b32 s46, s58, s44
	s_cselect_b32 s47, s56, s45
	s_cselect_b32 s44, 0, s8
	s_cselect_b32 s45, 0, s9
	s_add_u32 s8, s46, 0x8000
	s_addc_u32 s9, s47, 0
	s_add_u32 s44, s14, s44
	s_addc_u32 s45, s15, s45
	s_add_u32 s62, s6, s62
	s_addc_u32 s63, s7, s63
	s_add_u32 s62, s62, 0x4000
	s_addc_u32 s63, s63, 0
	s_sub_u32 s8, s62, 0x4000
	s_subb_u32 s9, s63, 0
	v_lshl_add_u64 v[164:165], s[8:9], 0, v[130:131]
	s_mov_b32 m0, s51
	s_nop 0
	global_load_lds_dwordx4 v[164:165], off
	v_lshl_add_u64 v[164:165], s[8:9], 0, v[134:135]
	s_mov_b32 m0, s57
	s_nop 0
	global_load_lds_dwordx4 v[164:165], off
	v_lshl_add_u64 v[164:165], s[62:63], 0, v[130:131]
	s_add_i32 m0, s30, 0xc000
	ds_read_b128 v[220:223], v186
	ds_read_b128 v[224:227], v186 offset:1024
	ds_read_b128 v[228:231], v186 offset:2048
	ds_read_b128 v[232:235], v186 offset:3072
	ds_read_b128 v[236:239], v186 offset:4096
	ds_read_b128 v[240:243], v186 offset:5120
	ds_read_b128 v[244:247], v186 offset:6144
	ds_read_b128 v[248:251], v186 offset:7168
	global_load_lds_dwordx4 v[164:165], off
	v_lshl_add_u64 v[164:165], s[62:63], 0, v[134:135]
	s_add_i32 m0, s30, 0xe000
	s_nop 0
	global_load_lds_dwordx4 v[164:165], off
	s_waitcnt vmcnt(8)
	s_waitcnt lgkmcnt(0)
	s_barrier
	s_setprio 1
	s_waitcnt lgkmcnt(0)
	v_mfma_f32_16x16x32_bf16 v[126:129], v[156:159], v[220:223], v[126:129]
	v_mfma_f32_16x16x32_bf16 v[126:129], v[160:163], v[224:227], v[126:129]
	v_mfma_f32_16x16x32_bf16 v[110:113], v[156:159], v[228:231], v[110:113]
	v_mfma_f32_16x16x32_bf16 v[110:113], v[160:163], v[232:235], v[110:113]
	v_mfma_f32_16x16x32_bf16 v[94:97], v[156:159], v[236:239], v[94:97]
	v_mfma_f32_16x16x32_bf16 v[94:97], v[160:163], v[240:243], v[94:97]
	v_mfma_f32_16x16x32_bf16 v[78:81], v[156:159], v[244:247], v[78:81]
	v_mfma_f32_16x16x32_bf16 v[78:81], v[160:163], v[248:251], v[78:81]
	v_mfma_f32_16x16x32_bf16 v[122:125], v[196:199], v[220:223], v[122:125]
	v_mfma_f32_16x16x32_bf16 v[122:125], v[200:203], v[224:227], v[122:125]
	v_mfma_f32_16x16x32_bf16 v[106:109], v[196:199], v[228:231], v[106:109]
	v_mfma_f32_16x16x32_bf16 v[106:109], v[200:203], v[232:235], v[106:109]
	v_mfma_f32_16x16x32_bf16 v[90:93], v[196:199], v[236:239], v[90:93]
	v_mfma_f32_16x16x32_bf16 v[90:93], v[200:203], v[240:243], v[90:93]
	v_mfma_f32_16x16x32_bf16 v[74:77], v[196:199], v[244:247], v[74:77]
	v_mfma_f32_16x16x32_bf16 v[74:77], v[200:203], v[248:251], v[74:77]
	s_setprio 0
	s_setprio 1
	v_mfma_f32_16x16x32_bf16 v[118:121], v[204:207], v[220:223], v[118:121]
	v_mfma_f32_16x16x32_bf16 v[118:121], v[208:211], v[224:227], v[118:121]
	v_mfma_f32_16x16x32_bf16 v[102:105], v[204:207], v[228:231], v[102:105]
	v_mfma_f32_16x16x32_bf16 v[102:105], v[208:211], v[232:235], v[102:105]
	v_mfma_f32_16x16x32_bf16 v[86:89], v[204:207], v[236:239], v[86:89]
	v_mfma_f32_16x16x32_bf16 v[86:89], v[208:211], v[240:243], v[86:89]
	v_mfma_f32_16x16x32_bf16 v[70:73], v[204:207], v[244:247], v[70:73]
	v_mfma_f32_16x16x32_bf16 v[70:73], v[208:211], v[248:251], v[70:73]
	v_mfma_f32_16x16x32_bf16 v[114:117], v[212:215], v[220:223], v[114:117]
	v_mfma_f32_16x16x32_bf16 v[114:117], v[216:219], v[224:227], v[114:117]
	v_mfma_f32_16x16x32_bf16 v[98:101], v[212:215], v[228:231], v[98:101]
	v_mfma_f32_16x16x32_bf16 v[98:101], v[216:219], v[232:235], v[98:101]
	v_mfma_f32_16x16x32_bf16 v[82:85], v[212:215], v[236:239], v[82:85]
	v_mfma_f32_16x16x32_bf16 v[82:85], v[216:219], v[240:243], v[82:85]
	v_mfma_f32_16x16x32_bf16 v[66:69], v[212:215], v[244:247], v[66:69]
	v_mfma_f32_16x16x32_bf16 v[66:69], v[216:219], v[248:251], v[66:69]
	s_setprio 0
	s_barrier
	s_add_i32 s62, s67, s29
	v_lshl_add_u64 v[164:165], s[44:45], 0, v[132:133]
	s_mov_b32 m0, s62
	ds_read_b128 v[220:223], v186 offset:16384
	ds_read_b128 v[224:227], v186 offset:17408
	ds_read_b128 v[228:231], v186 offset:18432
	ds_read_b128 v[232:235], v186 offset:19456
	ds_read_b128 v[236:239], v186 offset:20480
	ds_read_b128 v[240:243], v186 offset:21504
	ds_read_b128 v[244:247], v186 offset:22528
	ds_read_b128 v[248:251], v186 offset:23552
	global_load_lds_dwordx4 v[164:165], off
	s_add_i32 m0, s62, 0x2000
	s_add_u32 s62, s44, 0x4000
	v_lshl_add_u64 v[164:165], s[44:45], 0, v[136:137]
	s_addc_u32 s63, s45, 0
	s_add_i32 s72, s68, s29
	global_load_lds_dwordx4 v[164:165], off
	v_lshl_add_u64 v[164:165], s[62:63], 0, v[132:133]
	s_mov_b32 m0, s72
	s_nop 0
	global_load_lds_dwordx4 v[164:165], off
	v_lshl_add_u64 v[164:165], s[62:63], 0, v[136:137]
	s_add_i32 m0, s72, 0x2000
	s_nop 0
	global_load_lds_dwordx4 v[164:165], off
	s_waitcnt vmcnt(6)
	s_waitcnt lgkmcnt(0)
	s_barrier
; #define PG8_STAGE(bufoff, gbase, voff) do { _Pragma("unroll") for (int _i = 0; _i < 2; ++_i) \
;         __builtin_amdgcn_global_load_lds((const unsigned*)((const char*)(gbase) + (voff)[_i]), (PG8_LAS unsigned*)(lds + (bufoff) + ldsw + _i * 8192), 16, 0, 0); } while (0)
; #define PG8_LDA(dst, b, h) do { _Pragma("unroll") for (int m = 0; m < 4; ++m) _Pragma("unroll") for (int k = 0; k < 2; ++k) dst[m][k] = *(const PG8_LAS bf16x8*)(lds + PG8_SA(b, h) + aoff + m * 2048 + k * 1024); } while (0)
; #define PG8_LDB(dst, b, h) do { _Pragma("unroll") for (int n = 0; n < 2; ++n) _Pragma("unroll") for (int k = 0; k < 2; ++k) dst[n][k] = *(const PG8_LAS bf16x8*)(lds + PG8_SB(b, h) + boff + n * 2048 + k * 1024); } while (0)
; #define PG8_MMA(ai, bj, At, Bt) do { __builtin_amdgcn_s_setprio(1); _Pragma("unroll") for (int m = 0; m < 4; ++m) _Pragma("unroll") for (int n = 0; n < 2; ++n) _Pragma("unroll") for (int k = 0; k < 2; ++k) \
;         acc[ai][bj][m][n] = __builtin_amdgcn_mfma_f32_16x16x32_bf16(Bt[n][k], At[m][k], acc[ai][bj][m][n], 0, 0, 0); __builtin_amdgcn_s_setprio(0); } while (0)
; #define PG8_WAIT_V(n) asm volatile("s_waitcnt vmcnt(" #n ")" ::: "memory")
; #define PG8_WAIT_L(n) asm volatile("s_waitcnt lgkmcnt(" #n ")" ::: "memory")
; #define PG8_BAR __builtin_amdgcn_s_barrier()
; #define PG8_SCHED __builtin_amdgcn_sched_barrier(0)
; template <class Epi, class Sched, bool ALIGN_EPI = false, bool SP2 = false>
; __device__ __forceinline__ void gemm_phase(PG8_LAS unsigned char* lds, const Gemm g, const Sched& S, const Epi& E) {
;     ...
;             PG8_WAIT_V(8); PG8_WAIT_L(0); PG8_BAR; PG8_MMA(1, 0, At, B0); PG8_MMA(1, 1, At, B1); PG8_BAR; PG8_SCHED;
;             PG8_LDB(B0, 1, 0); PG8_LDB(B1, 1, 1); PG8_SCHED; PG8_LDA(At, 1, 0); PG8_STAGE(PG8_SA(0, 1), a2 + hstep, voffA);
;             PG8_WAIT_V(8); PG8_WAIT_L(0); PG8_BAR; PG8_MMA(0, 0, At, B0); PG8_MMA(0, 1, At, B1); PG8_BAR; PG8_SCHED;
	s_setprio 1
	s_waitcnt lgkmcnt(0)
	v_mfma_f32_16x16x32_bf16 v[62:65], v[156:159], v[220:223], v[62:65]
	v_mfma_f32_16x16x32_bf16 v[62:65], v[160:163], v[224:227], v[62:65]
	v_mfma_f32_16x16x32_bf16 v[46:49], v[156:159], v[228:231], v[46:49]
	v_mfma_f32_16x16x32_bf16 v[46:49], v[160:163], v[232:235], v[46:49]
	v_mfma_f32_16x16x32_bf16 v[30:33], v[156:159], v[236:239], v[30:33]
	v_mfma_f32_16x16x32_bf16 v[30:33], v[160:163], v[240:243], v[30:33]
	v_mfma_f32_16x16x32_bf16 v[14:17], v[156:159], v[244:247], v[14:17]
	v_mfma_f32_16x16x32_bf16 v[14:17], v[160:163], v[248:251], v[14:17]
	v_mfma_f32_16x16x32_bf16 v[58:61], v[196:199], v[220:223], v[58:61]
	v_mfma_f32_16x16x32_bf16 v[58:61], v[200:203], v[224:227], v[58:61]
	v_mfma_f32_16x16x32_bf16 v[42:45], v[196:199], v[228:231], v[42:45]
	v_mfma_f32_16x16x32_bf16 v[42:45], v[200:203], v[232:235], v[42:45]
	v_mfma_f32_16x16x32_bf16 v[26:29], v[196:199], v[236:239], v[26:29]
	v_mfma_f32_16x16x32_bf16 v[26:29], v[200:203], v[240:243], v[26:29]
	v_mfma_f32_16x16x32_bf16 v[10:13], v[196:199], v[244:247], v[10:13]
	v_mfma_f32_16x16x32_bf16 v[10:13], v[200:203], v[248:251], v[10:13]
	s_setprio 0
	s_setprio 1
	v_mfma_f32_16x16x32_bf16 v[54:57], v[204:207], v[220:223], v[54:57]
	v_mfma_f32_16x16x32_bf16 v[54:57], v[208:211], v[224:227], v[54:57]
	v_mfma_f32_16x16x32_bf16 v[38:41], v[204:207], v[228:231], v[38:41]
	v_mfma_f32_16x16x32_bf16 v[38:41], v[208:211], v[232:235], v[38:41]
	v_mfma_f32_16x16x32_bf16 v[22:25], v[204:207], v[236:239], v[22:25]
	v_mfma_f32_16x16x32_bf16 v[22:25], v[208:211], v[240:243], v[22:25]
	v_mfma_f32_16x16x32_bf16 v[6:9], v[204:207], v[244:247], v[6:9]
	v_mfma_f32_16x16x32_bf16 v[6:9], v[208:211], v[248:251], v[6:9]
	v_mfma_f32_16x16x32_bf16 v[50:53], v[212:215], v[220:223], v[50:53]
	v_mfma_f32_16x16x32_bf16 v[50:53], v[216:219], v[224:227], v[50:53]
	v_mfma_f32_16x16x32_bf16 v[34:37], v[212:215], v[228:231], v[34:37]
	v_mfma_f32_16x16x32_bf16 v[34:37], v[216:219], v[232:235], v[34:37]
	v_mfma_f32_16x16x32_bf16 v[18:21], v[212:215], v[236:239], v[18:21]
	v_mfma_f32_16x16x32_bf16 v[18:21], v[216:219], v[240:243], v[18:21]
	v_mfma_f32_16x16x32_bf16 v[2:5], v[212:215], v[244:247], v[2:5]
	v_mfma_f32_16x16x32_bf16 v[2:5], v[216:219], v[248:251], v[2:5]
	s_setprio 0
	s_barrier
	s_add_i32 s62, 0, 0x18000
	v_add_u32_e32 v145, s62, v166
	s_add_i32 s63, 0, 0x1c000
	ds_read_b128 v[156:159], v145
	ds_read_b128 v[160:163], v145 offset:1024
	ds_read_b128 v[196:199], v145 offset:2048
	ds_read_b128 v[200:203], v145 offset:3072
	v_add_u32_e32 v145, s63, v166
	ds_read_b128 v[204:207], v145
	ds_read_b128 v[208:211], v145 offset:1024
	ds_read_b128 v[212:215], v145 offset:2048
	ds_read_b128 v[216:219], v145 offset:3072
	v_lshl_add_u64 v[164:165], s[46:47], 0, v[130:131]
	s_mov_b32 m0, s30
	s_nop 0
	global_load_lds_dwordx4 v[164:165], off
	v_lshl_add_u64 v[164:165], s[46:47], 0, v[134:135]
	s_mov_b32 m0, s31
	s_nop 0
	global_load_lds_dwordx4 v[164:165], off
	s_add_u32 s46, s46, 0x4000
	s_addc_u32 s47, s47, 0
	s_mov_b32 m0, s35
	v_lshl_add_u64 v[164:165], s[46:47], 0, v[130:131]
	ds_read_b128 v[220:223], v186 offset:32768
	ds_read_b128 v[224:227], v186 offset:33792
	ds_read_b128 v[228:231], v186 offset:34816
	ds_read_b128 v[232:235], v186 offset:35840
	ds_read_b128 v[236:239], v186 offset:36864
	ds_read_b128 v[240:243], v186 offset:37888
	ds_read_b128 v[244:247], v186 offset:38912
	ds_read_b128 v[248:251], v186 offset:39936
	global_load_lds_dwordx4 v[164:165], off
	v_lshl_add_u64 v[164:165], s[46:47], 0, v[134:135]
	s_mov_b32 m0, s48
	s_nop 0
	global_load_lds_dwordx4 v[164:165], off
	s_waitcnt vmcnt(8)
	s_waitcnt lgkmcnt(0)
	s_barrier
; #define PG8_STAGE(bufoff, gbase, voff) do { _Pragma("unroll") for (int _i = 0; _i < 2; ++_i) \
;         __builtin_amdgcn_global_load_lds((const unsigned*)((const char*)(gbase) + (voff)[_i]), (PG8_LAS unsigned*)(lds + (bufoff) + ldsw + _i * 8192), 16, 0, 0); } while (0)
; #define PG8_LDA(dst, b, h) do { _Pragma("unroll") for (int m = 0; m < 4; ++m) _Pragma("unroll") for (int k = 0; k < 2; ++k) dst[m][k] = *(const PG8_LAS bf16x8*)(lds + PG8_SA(b, h) + aoff + m * 2048 + k * 1024); } while (0)
; #define PG8_MMA(ai, bj, At, Bt) do { __builtin_amdgcn_s_setprio(1); _Pragma("unroll") for (int m = 0; m < 4; ++m) _Pragma("unroll") for (int n = 0; n < 2; ++n) _Pragma("unroll") for (int k = 0; k < 2; ++k) \
;         acc[ai][bj][m][n] = __builtin_amdgcn_mfma_f32_16x16x32_bf16(Bt[n][k], At[m][k], acc[ai][bj][m][n], 0, 0, 0); __builtin_amdgcn_s_setprio(0); } while (0)
; #define PG8_WAIT_V(n) asm volatile("s_waitcnt vmcnt(" #n ")" ::: "memory")
; #define PG8_WAIT_L(n) asm volatile("s_waitcnt lgkmcnt(" #n ")" ::: "memory")
; #define PG8_BAR __builtin_amdgcn_s_barrier()
; #define PG8_SCHED __builtin_amdgcn_sched_barrier(0)
; template <class Epi, class Sched, bool ALIGN_EPI = false, bool SP2 = false>
; __device__ __forceinline__ void gemm_phase(PG8_LAS unsigned char* lds, const Gemm g, const Sched& S, const Epi& E) {
;     ...
;             PG8_WAIT_V(8); PG8_WAIT_L(0); PG8_BAR; PG8_MMA(0, 0, At, B0); PG8_MMA(0, 1, At, B1); PG8_BAR; PG8_SCHED;
;             PG8_LDA(At, 1, 1); PG8_STAGE(PG8_SB(1, 0), b3, voffB); PG8_STAGE(PG8_SB(1, 1), b3 + hstep, voffB); PG8_STAGE(PG8_SA(1, 0), a3, voffA);
;             PG8_WAIT_V(8); PG8_WAIT_L(0); PG8_BAR; PG8_MMA(1, 0, At, B0); PG8_MMA(1, 1, At, B1); PG8_BAR; PG8_SCHED;
;     ...
;         }
;         if constexpr (Epi::HAS_MID) { if (seg == 0) E.mid(acc, cur, wr, wc, fr, fq); }
;         }
;         if constexpr (ALIGN_EPI) { if (wr == 0) PG8_BAR; }
	s_setprio 1
	s_waitcnt lgkmcnt(0)
	v_mfma_f32_16x16x32_bf16 v[126:129], v[156:159], v[220:223], v[126:129]
	v_mfma_f32_16x16x32_bf16 v[126:129], v[160:163], v[224:227], v[126:129]
	v_mfma_f32_16x16x32_bf16 v[110:113], v[156:159], v[228:231], v[110:113]
	v_mfma_f32_16x16x32_bf16 v[110:113], v[160:163], v[232:235], v[110:113]
	v_mfma_f32_16x16x32_bf16 v[94:97], v[156:159], v[236:239], v[94:97]
	v_mfma_f32_16x16x32_bf16 v[94:97], v[160:163], v[240:243], v[94:97]
	v_mfma_f32_16x16x32_bf16 v[78:81], v[156:159], v[244:247], v[78:81]
	v_mfma_f32_16x16x32_bf16 v[78:81], v[160:163], v[248:251], v[78:81]
	v_mfma_f32_16x16x32_bf16 v[122:125], v[196:199], v[220:223], v[122:125]
	v_mfma_f32_16x16x32_bf16 v[122:125], v[200:203], v[224:227], v[122:125]
	v_mfma_f32_16x16x32_bf16 v[106:109], v[196:199], v[228:231], v[106:109]
	v_mfma_f32_16x16x32_bf16 v[106:109], v[200:203], v[232:235], v[106:109]
	v_mfma_f32_16x16x32_bf16 v[90:93], v[196:199], v[236:239], v[90:93]
	v_mfma_f32_16x16x32_bf16 v[90:93], v[200:203], v[240:243], v[90:93]
	v_mfma_f32_16x16x32_bf16 v[74:77], v[196:199], v[244:247], v[74:77]
	v_mfma_f32_16x16x32_bf16 v[74:77], v[200:203], v[248:251], v[74:77]
	s_setprio 0
	s_setprio 1
	v_mfma_f32_16x16x32_bf16 v[118:121], v[204:207], v[220:223], v[118:121]
	v_mfma_f32_16x16x32_bf16 v[118:121], v[208:211], v[224:227], v[118:121]
	v_mfma_f32_16x16x32_bf16 v[102:105], v[204:207], v[228:231], v[102:105]
	v_mfma_f32_16x16x32_bf16 v[102:105], v[208:211], v[232:235], v[102:105]
	v_mfma_f32_16x16x32_bf16 v[86:89], v[204:207], v[236:239], v[86:89]
	v_mfma_f32_16x16x32_bf16 v[86:89], v[208:211], v[240:243], v[86:89]
	v_mfma_f32_16x16x32_bf16 v[70:73], v[204:207], v[244:247], v[70:73]
	v_mfma_f32_16x16x32_bf16 v[70:73], v[208:211], v[248:251], v[70:73]
	v_mfma_f32_16x16x32_bf16 v[114:117], v[212:215], v[220:223], v[114:117]
	v_mfma_f32_16x16x32_bf16 v[114:117], v[216:219], v[224:227], v[114:117]
	v_mfma_f32_16x16x32_bf16 v[98:101], v[212:215], v[228:231], v[98:101]
	v_mfma_f32_16x16x32_bf16 v[98:101], v[216:219], v[232:235], v[98:101]
	v_mfma_f32_16x16x32_bf16 v[82:85], v[212:215], v[236:239], v[82:85]
	v_mfma_f32_16x16x32_bf16 v[82:85], v[216:219], v[240:243], v[82:85]
	v_mfma_f32_16x16x32_bf16 v[66:69], v[212:215], v[244:247], v[66:69]
	v_mfma_f32_16x16x32_bf16 v[66:69], v[216:219], v[248:251], v[66:69]
	s_setprio 0
	s_barrier
	s_add_u32 s46, s44, 0x8000
	s_addc_u32 s47, s45, 0
	s_add_i32 s62, s62, s29
	v_lshl_add_u64 v[164:165], s[46:47], 0, v[132:133]
	s_mov_b32 m0, s62
	ds_read_b128 v[220:223], v186 offset:49152
	ds_read_b128 v[224:227], v186 offset:50176
	ds_read_b128 v[228:231], v186 offset:51200
	ds_read_b128 v[232:235], v186 offset:52224
	ds_read_b128 v[236:239], v186 offset:53248
	ds_read_b128 v[240:243], v186 offset:54272
	ds_read_b128 v[244:247], v186 offset:55296
	ds_read_b128 v[248:251], v186 offset:56320
	global_load_lds_dwordx4 v[164:165], off
	s_add_i32 m0, s62, 0x2000
	s_add_u32 s44, s44, 0xc000
	v_lshl_add_u64 v[164:165], s[46:47], 0, v[136:137]
	s_addc_u32 s45, s45, 0
	s_add_i32 s46, s63, s29
	global_load_lds_dwordx4 v[164:165], off
	v_lshl_add_u64 v[164:165], s[44:45], 0, v[132:133]
	s_mov_b32 m0, s46
	s_nop 0
	global_load_lds_dwordx4 v[164:165], off
	v_lshl_add_u64 v[164:165], s[44:45], 0, v[136:137]
	s_add_i32 m0, s46, 0x2000
	s_nop 0
	global_load_lds_dwordx4 v[164:165], off
	s_waitcnt vmcnt(6)
	s_waitcnt lgkmcnt(0)
	s_barrier
	s_setprio 1
	s_waitcnt lgkmcnt(0)
	v_mfma_f32_16x16x32_bf16 v[62:65], v[156:159], v[220:223], v[62:65]
	v_mfma_f32_16x16x32_bf16 v[62:65], v[160:163], v[224:227], v[62:65]
	v_mfma_f32_16x16x32_bf16 v[46:49], v[156:159], v[228:231], v[46:49]
	v_mfma_f32_16x16x32_bf16 v[46:49], v[160:163], v[232:235], v[46:49]
	v_mfma_f32_16x16x32_bf16 v[30:33], v[156:159], v[236:239], v[30:33]
	v_mfma_f32_16x16x32_bf16 v[30:33], v[160:163], v[240:243], v[30:33]
	v_mfma_f32_16x16x32_bf16 v[14:17], v[156:159], v[244:247], v[14:17]
	v_mfma_f32_16x16x32_bf16 v[14:17], v[160:163], v[248:251], v[14:17]
	v_mfma_f32_16x16x32_bf16 v[58:61], v[196:199], v[220:223], v[58:61]
	v_mfma_f32_16x16x32_bf16 v[58:61], v[200:203], v[224:227], v[58:61]
	v_mfma_f32_16x16x32_bf16 v[42:45], v[196:199], v[228:231], v[42:45]
	v_mfma_f32_16x16x32_bf16 v[42:45], v[200:203], v[232:235], v[42:45]
	v_mfma_f32_16x16x32_bf16 v[26:29], v[196:199], v[236:239], v[26:29]
	v_mfma_f32_16x16x32_bf16 v[26:29], v[200:203], v[240:243], v[26:29]
	v_mfma_f32_16x16x32_bf16 v[10:13], v[196:199], v[244:247], v[10:13]
	v_mfma_f32_16x16x32_bf16 v[10:13], v[200:203], v[248:251], v[10:13]
	s_setprio 0
	s_setprio 1
	v_mfma_f32_16x16x32_bf16 v[54:57], v[204:207], v[220:223], v[54:57]
	v_mfma_f32_16x16x32_bf16 v[54:57], v[208:211], v[224:227], v[54:57]
	v_mfma_f32_16x16x32_bf16 v[38:41], v[204:207], v[228:231], v[38:41]
	v_mfma_f32_16x16x32_bf16 v[38:41], v[208:211], v[232:235], v[38:41]
	v_mfma_f32_16x16x32_bf16 v[22:25], v[204:207], v[236:239], v[22:25]
	v_mfma_f32_16x16x32_bf16 v[22:25], v[208:211], v[240:243], v[22:25]
	v_mfma_f32_16x16x32_bf16 v[6:9], v[204:207], v[244:247], v[6:9]
	v_mfma_f32_16x16x32_bf16 v[6:9], v[208:211], v[248:251], v[6:9]
	v_mfma_f32_16x16x32_bf16 v[50:53], v[212:215], v[220:223], v[50:53]
	v_mfma_f32_16x16x32_bf16 v[50:53], v[216:219], v[224:227], v[50:53]
	v_mfma_f32_16x16x32_bf16 v[34:37], v[212:215], v[228:231], v[34:37]
	v_mfma_f32_16x16x32_bf16 v[34:37], v[216:219], v[232:235], v[34:37]
	v_mfma_f32_16x16x32_bf16 v[18:21], v[212:215], v[236:239], v[18:21]
	v_mfma_f32_16x16x32_bf16 v[18:21], v[216:219], v[240:243], v[18:21]
	v_mfma_f32_16x16x32_bf16 v[2:5], v[212:215], v[244:247], v[2:5]
	v_mfma_f32_16x16x32_bf16 v[2:5], v[216:219], v[248:251], v[2:5]
	s_setprio 0
	s_barrier
	s_cmpk_gt_u32 s59, 0xa9
	s_mov_b32 s59, s24
	s_cbranch_scc0 .LBB0_939
	s_and_b64 vcc, exec, s[38:39]
	s_cbranch_vccz .LBB0_942
	s_barrier
